# phase-1 GEMM k-loop rewritten with v_mfma_f32_16x16x32_bf16 (4x4 sub-tiles/wave), swizzled 128B-row LDS layout, coalesced loader, new acc->ct write
# speedup vs baseline: 1.0568x; 1.0087x over previous
.LBB0_174:
	s_or_b64 exec, exec, s[4:5]
	v_bfe_u32 v151, v100, 5, 1
	s_cmpk_gt_i32 s2, 0x98f
	v_lshrrev_b32_e32 v147, 5, v100
	v_lshlrev_b32_e32 v111, 6, v100
	v_lshlrev_b32_e32 v148, 4, v151
	v_lshlrev_b32_e32 v149, 2, v100
	s_waitcnt lgkmcnt(0)
	s_barrier
	s_cbranch_scc1 .LBB0_223
	v_and_b32_e32 v0, 0x1c0, v105
	v_or_b32_e32 v1, v0, v101
	v_lshl_or_b32 v0, v151, 2, v0
	s_movk_i32 s0, 0x90
	v_and_b32_e32 v2, 0x5f, v100
	v_mul_u32_u24_e32 v0, 0x84, v0
	v_and_b32_e32 v64, 64, v111
	v_mul_u32_u24_e32 v3, 0x90, v2
	v_mad_u32_u24 v76, v1, s0, v148
	v_mul_i32_i24_e32 v1, 0xffffff74, v2
	v_lshlrev_b32_e32 v0, 2, v0
	v_mad_u32_u24 v74, v105, s0, v64
	v_mad_u32_u24 v75, v2, s0, v148
	v_add3_u32 v77, v3, v1, v0
	s_movk_i32 s0, 0xe0
	v_and_b32_e32 v0, 0xe0, v100
	v_cmp_eq_u32_e32 vcc, s0, v0
	v_readlane_b32 s36, v238, 48
	v_add_u32_e32 v0, 0x300, v100
	v_mov_b32_e32 v65, 0
	v_readlane_b32 s37, v238, 49
	v_readlane_b32 s38, v238, 50
	v_readlane_b32 s39, v238, 51
	v_readlane_b32 s40, v238, 52
	v_readlane_b32 s41, v238, 53
	v_readlane_b32 s42, v238, 54
	v_readlane_b32 s43, v238, 55
	v_readlane_b32 s44, v238, 56
	v_readlane_b32 s45, v238, 57
	v_readlane_b32 s46, v238, 58
	v_readlane_b32 s47, v238, 59
	v_readlane_b32 s48, v238, 60
	v_readlane_b32 s49, v238, 61
	v_readlane_b32 s50, v238, 62
	v_readlane_b32 s51, v238, 63
	v_lshrrev_b32_e32 v79, 5, v0
	v_add_u32_e32 v0, 0x200, v100
	v_lshl_add_u64 v[66:67], s[44:45], 0, v[64:65]
	v_readlane_b32 s36, v238, 16
	v_lshrrev_b32_e32 v81, 5, v0
	v_add_u32_e32 v0, 0x100, v100
	v_readlane_b32 s48, v238, 28
	v_readlane_b32 s49, v238, 29
	s_movk_i32 s0, 0x210
	v_lshrrev_b32_e32 v83, 5, v0
	v_and_b32_e32 v78, 0x7c, v149
	v_lshl_add_u64 v[68:69], s[48:49], 0, v[64:65]
	v_lshrrev_b32_e32 v69, 3, v100
	v_and_b32_e32 v68, 7, v100
	v_bfe_u32 v244, v100, 4, 3
	v_xor_b32_e32 v244, v244, v68
	v_lshlrev_b32_e32 v244, 4, v244
	v_lshl_or_b32 v74, v69, 7, v244
	v_lshlrev_b32_e32 v245, 4, v68
	v_lshl_or_b32 v66, v69, 11, v245
	v_add_u32_e32 v67, 0x10000, v66
	v_add_u32_e32 v68, 0x20000, v66
	v_add_u32_e32 v69, 0x30000, v66
	v_and_b32_e32 v244, 15, v100
	v_bfe_u32 v245, v100, 4, 2
	v_bfe_u32 v246, v100, 1, 3
	v_xor_b32_e32 v247, v245, v246
	v_lshlrev_b32_e32 v247, 4, v247
	v_lshl_or_b32 v247, v244, 7, v247
	v_bfe_u32 v246, v100, 7, 1
	v_lshl_add_u32 v239, v246, 13, v247
	v_xor_b32_e32 v240, 64, v239
	v_bfe_u32 v246, v100, 6, 1
	v_lshl_add_u32 v241, v246, 13, v247
	v_add_u32_e32 v241, 0x4000, v241
	v_xor_b32_e32 v242, 64, v241
	v_bfe_u32 v247, v100, 7, 1
	v_lshlrev_b32_e32 v247, 6, v247
	v_lshl_add_u32 v247, v245, 2, v247
	v_mul_u32_u24_e32 v247, 0x84, v247
	v_lshl_add_u32 v247, v246, 6, v247
	v_add_u32_e32 v247, v247, v244
	v_lshlrev_b32_e32 v243, 2, v247
	v_mad_u32_u24 v80, v79, s0, v98
	v_mad_u32_u24 v82, v81, s0, v98
	v_mad_u32_u24 v84, v83, s0, v98
	v_mad_u32_u24 v85, v147, s0, v98
	s_movk_i32 s0, 0x1200
	s_movk_i32 s1, 0x7fff
	s_movk_i32 s3, 0x3fff
	s_movk_i32 s11, 0x700
	s_movk_i32 s62, 0x7ff
	v_add_u32_e32 v86, 0x400, v77
	v_add_u32_e32 v87, 0x1000, v77
	v_add_u32_e32 v88, 0x1400, v77
	v_add_u32_e32 v89, 0x2000, v77
	v_add_u32_e32 v90, 0x2400, v77
	v_add_u32_e32 v91, 0x3000, v77
	v_add_u32_e32 v92, 0x3200, v77
	v_add_u32_e32 v93, 0x3400, v77
	v_add_u32_e32 v94, 0x3600, v77
	v_add_u32_e32 v95, 0x4000, v77
	v_add_u32_e32 v97, 0x4400, v77
	v_add_u32_e32 v99, 0x4800, v77
	v_add_u32_e32 v103, 0x5000, v77
	v_add_u32_e32 v108, 0x5400, v77
	v_add_u32_e32 v109, 0x5800, v77
	v_add_u32_e32 v110, 0x6000, v77
	v_add_u32_e32 v112, 0x6400, v77
	v_add_u32_e32 v113, 0x6800, v77
	v_add_u32_e32 v114, 0x7200, v77
	v_add_u32_e32 v115, 0x7400, v77
	v_add_u32_e32 v116, 0x7600, v77
	v_add_u32_e32 v117, 0x7800, v77
	v_mov_b32_e32 v118, 1
	s_mov_b32 s63, s2
	v_readlane_b32 s37, v238, 17
	v_readlane_b32 s38, v238, 18
	v_readlane_b32 s39, v238, 19
	v_readlane_b32 s40, v238, 20
	v_readlane_b32 s41, v238, 21
	v_readlane_b32 s42, v238, 22
	v_readlane_b32 s43, v238, 23
	v_readlane_b32 s44, v238, 24
	v_readlane_b32 s45, v238, 25
	v_readlane_b32 s46, v238, 26
	v_readlane_b32 s47, v238, 27
	v_readlane_b32 s50, v238, 30
	v_readlane_b32 s51, v238, 31
	s_branch .LBB0_177

.LBB0_177:
	s_mul_hi_i32 s4, s63, 0x38e38e39
	s_lshr_b32 s5, s4, 31
	s_ashr_i32 s4, s4, 2
	s_add_i32 s4, s4, s5
	s_mul_i32 s5, s4, 18
	s_sub_i32 s5, s63, s5
	s_lshl_b32 s6, s4, 7
	s_lshl_b32 s4, s5, 7
	v_readlane_b32 s98, v238, 56
	v_readlane_b32 s99, v238, 57
	v_readlane_b32 s100, v238, 28
	v_readlane_b32 s101, v238, 29
	s_lshl_b32 s5, s6, 11
	s_nop 0
	s_add_u32 s98, s98, s5
	s_addc_u32 s99, s99, 0
	s_lshl_b32 s5, s4, 11
	s_add_u32 s100, s100, s5
	s_addc_u32 s101, s101, 0
	s_nop 1
	global_load_dwordx4 v[172:175], v66, s[98:99]
	global_load_dwordx4 v[176:179], v67, s[98:99]
	global_load_dwordx4 v[180:183], v68, s[98:99]
	global_load_dwordx4 v[184:187], v69, s[98:99]
	global_load_dwordx4 v[188:191], v66, s[100:101]
	global_load_dwordx4 v[192:195], v67, s[100:101]
	global_load_dwordx4 v[196:199], v68, s[100:101]
	global_load_dwordx4 v[200:203], v69, s[100:101]
	global_load_dwordx4 v[204:207], v66, s[98:99] offset:128
	global_load_dwordx4 v[208:211], v67, s[98:99] offset:128
	global_load_dwordx4 v[212:215], v68, s[98:99] offset:128
	global_load_dwordx4 v[216:219], v69, s[98:99] offset:128
	global_load_dwordx4 v[220:223], v66, s[100:101] offset:128
	global_load_dwordx4 v[224:227], v67, s[100:101] offset:128
	global_load_dwordx4 v[228:231], v68, s[100:101] offset:128
	global_load_dwordx4 v[232:235], v69, s[100:101] offset:128
	v_readlane_b32 s12, v238, 32
	v_readlane_b32 s36, v238, 16
	v_readlane_b32 s13, v238, 33
	v_readlane_b32 s14, v238, 34
	v_readlane_b32 s38, v238, 18
	v_readlane_b32 s39, v238, 19
	s_mov_b32 s14, 0
	v_readlane_b32 s15, v238, 35
	v_readlane_b32 s16, v238, 36
	v_readlane_b32 s17, v238, 37
	v_readlane_b32 s18, v238, 38
	v_readlane_b32 s19, v238, 39
	v_readlane_b32 s20, v238, 40
	v_readlane_b32 s21, v238, 41
	v_readlane_b32 s22, v238, 42
	v_readlane_b32 s23, v238, 43
	v_readlane_b32 s24, v238, 44
	v_readlane_b32 s25, v238, 45
	v_readlane_b32 s26, v238, 46
	v_readlane_b32 s27, v238, 47
	v_readlane_b32 s37, v238, 17
	v_readlane_b32 s40, v238, 20
	v_readlane_b32 s41, v238, 21
	v_readlane_b32 s42, v238, 22
	v_readlane_b32 s43, v238, 23
	v_readlane_b32 s44, v238, 24
	v_readlane_b32 s45, v238, 25
	v_readlane_b32 s46, v238, 26
	v_readlane_b32 s47, v238, 27
	v_readlane_b32 s48, v238, 28
	v_readlane_b32 s49, v238, 29
	v_readlane_b32 s50, v238, 30
	v_readlane_b32 s51, v238, 31
	s_barrier
	s_waitcnt vmcnt(8)
	ds_write_b128 v74, v[172:175]
	ds_write_b128 v74, v[176:179] offset:4096
	ds_write_b128 v74, v[180:183] offset:8192
	ds_write_b128 v74, v[184:187] offset:12288
	ds_write_b128 v74, v[188:191] offset:16384
	ds_write_b128 v74, v[192:195] offset:20480
	ds_write_b128 v74, v[196:199] offset:24576
	ds_write_b128 v74, v[200:203] offset:28672
	global_load_dwordx4 v[172:175], v66, s[98:99] offset:256
	global_load_dwordx4 v[176:179], v67, s[98:99] offset:256
	global_load_dwordx4 v[180:183], v68, s[98:99] offset:256
	global_load_dwordx4 v[184:187], v69, s[98:99] offset:256
	global_load_dwordx4 v[188:191], v66, s[100:101] offset:256
	global_load_dwordx4 v[192:195], v67, s[100:101] offset:256
	global_load_dwordx4 v[196:199], v68, s[100:101] offset:256
	global_load_dwordx4 v[200:203], v69, s[100:101] offset:256
	s_waitcnt lgkmcnt(0)
	s_barrier
	ds_read_b128 v[120:123], v239
	ds_read_b128 v[140:143], v241
	ds_read_b128 v[152:155], v241 offset:2048
	ds_read_b128 v[156:159], v241 offset:4096
	ds_read_b128 v[160:163], v241 offset:6144
	ds_read_b128 v[124:127], v239 offset:2048
	ds_read_b128 v[128:131], v239 offset:4096
	ds_read_b128 v[132:135], v239 offset:6144
	s_waitcnt lgkmcnt(6)
	v_mfma_f32_16x16x32_bf16 v[0:3], v[120:123], v[140:143], 0
	ds_read_b128 v[164:167], v240
	s_waitcnt lgkmcnt(6)
	v_mfma_f32_16x16x32_bf16 v[4:7], v[120:123], v[152:155], 0
	ds_read_b128 v[86:89], v242
	s_waitcnt lgkmcnt(6)
	v_mfma_f32_16x16x32_bf16 v[8:11], v[120:123], v[156:159], 0
	ds_read_b128 v[90:93], v242 offset:2048
	s_waitcnt lgkmcnt(6)
	v_mfma_f32_16x16x32_bf16 v[12:15], v[120:123], v[160:163], 0
	ds_read_b128 v[112:115], v242 offset:4096
	s_waitcnt lgkmcnt(6)
	v_mfma_f32_16x16x32_bf16 v[16:19], v[124:127], v[140:143], 0
	ds_read_b128 v[252:255], v242 offset:6144
	v_mfma_f32_16x16x32_bf16 v[20:23], v[124:127], v[152:155], 0
	ds_read_b128 v[168:171], v240 offset:2048
	v_mfma_f32_16x16x32_bf16 v[24:27], v[124:127], v[156:159], 0
	ds_read_b128 v[244:247], v240 offset:4096
	v_mfma_f32_16x16x32_bf16 v[28:31], v[124:127], v[160:163], 0
	ds_read_b128 v[248:251], v240 offset:6144
	s_waitcnt lgkmcnt(9)
	v_mfma_f32_16x16x32_bf16 v[32:35], v[128:131], v[140:143], 0
	v_mfma_f32_16x16x32_bf16 v[36:39], v[128:131], v[152:155], 0
	v_mfma_f32_16x16x32_bf16 v[40:43], v[128:131], v[156:159], 0
	v_mfma_f32_16x16x32_bf16 v[44:47], v[128:131], v[160:163], 0
	s_waitcnt lgkmcnt(8)
	v_mfma_f32_16x16x32_bf16 v[48:51], v[132:135], v[140:143], 0
	v_mfma_f32_16x16x32_bf16 v[52:55], v[132:135], v[152:155], 0
	v_mfma_f32_16x16x32_bf16 v[56:59], v[132:135], v[156:159], 0
	v_mfma_f32_16x16x32_bf16 v[60:63], v[132:135], v[160:163], 0
	s_waitcnt lgkmcnt(6)
	v_mfma_f32_16x16x32_bf16 v[0:3], v[164:167], v[86:89], v[0:3]
	s_waitcnt vmcnt(8)
	ds_write_b128 v74, v[204:207] offset:32768
	s_waitcnt lgkmcnt(6)
	v_mfma_f32_16x16x32_bf16 v[4:7], v[164:167], v[90:93], v[4:7]
	ds_write_b128 v74, v[208:211] offset:36864
	s_waitcnt lgkmcnt(6)
	v_mfma_f32_16x16x32_bf16 v[8:11], v[164:167], v[112:115], v[8:11]
	ds_write_b128 v74, v[212:215] offset:40960
	s_waitcnt lgkmcnt(6)
	v_mfma_f32_16x16x32_bf16 v[12:15], v[164:167], v[252:255], v[12:15]
	ds_write_b128 v74, v[216:219] offset:45056
	s_waitcnt lgkmcnt(6)
	v_mfma_f32_16x16x32_bf16 v[16:19], v[168:171], v[86:89], v[16:19]
	ds_write_b128 v74, v[220:223] offset:49152
	v_mfma_f32_16x16x32_bf16 v[20:23], v[168:171], v[90:93], v[20:23]
	ds_write_b128 v74, v[224:227] offset:53248
	v_mfma_f32_16x16x32_bf16 v[24:27], v[168:171], v[112:115], v[24:27]
	ds_write_b128 v74, v[228:231] offset:57344
	v_mfma_f32_16x16x32_bf16 v[28:31], v[168:171], v[252:255], v[28:31]
	ds_write_b128 v74, v[232:235] offset:61440
	s_waitcnt lgkmcnt(9)
	v_mfma_f32_16x16x32_bf16 v[32:35], v[244:247], v[86:89], v[32:35]
	global_load_dwordx4 v[204:207], v66, s[98:99] offset:384
	v_mfma_f32_16x16x32_bf16 v[36:39], v[244:247], v[90:93], v[36:39]
	global_load_dwordx4 v[208:211], v67, s[98:99] offset:384
	v_mfma_f32_16x16x32_bf16 v[40:43], v[244:247], v[112:115], v[40:43]
	global_load_dwordx4 v[212:215], v68, s[98:99] offset:384
	v_mfma_f32_16x16x32_bf16 v[44:47], v[244:247], v[252:255], v[44:47]
	global_load_dwordx4 v[216:219], v69, s[98:99] offset:384
	s_waitcnt lgkmcnt(8)
	v_mfma_f32_16x16x32_bf16 v[48:51], v[248:251], v[86:89], v[48:51]
	global_load_dwordx4 v[220:223], v66, s[100:101] offset:384
	v_mfma_f32_16x16x32_bf16 v[52:55], v[248:251], v[90:93], v[52:55]
	global_load_dwordx4 v[224:227], v67, s[100:101] offset:384
	v_mfma_f32_16x16x32_bf16 v[56:59], v[248:251], v[112:115], v[56:59]
	global_load_dwordx4 v[228:231], v68, s[100:101] offset:384
	v_mfma_f32_16x16x32_bf16 v[60:63], v[248:251], v[252:255], v[60:63]
	global_load_dwordx4 v[232:235], v69, s[100:101] offset:384
	s_waitcnt lgkmcnt(0)
	s_barrier
	ds_read_b128 v[120:123], v239 offset:32768
	ds_read_b128 v[140:143], v241 offset:32768
	ds_read_b128 v[152:155], v241 offset:34816
	ds_read_b128 v[156:159], v241 offset:36864
	ds_read_b128 v[160:163], v241 offset:38912
	ds_read_b128 v[124:127], v239 offset:34816
	ds_read_b128 v[128:131], v239 offset:36864
	ds_read_b128 v[132:135], v239 offset:38912
	s_waitcnt lgkmcnt(6)
	v_mfma_f32_16x16x32_bf16 v[0:3], v[120:123], v[140:143], v[0:3]
	ds_read_b128 v[164:167], v240 offset:32768
	s_waitcnt lgkmcnt(6)
	v_mfma_f32_16x16x32_bf16 v[4:7], v[120:123], v[152:155], v[4:7]
	ds_read_b128 v[86:89], v242 offset:32768
	s_waitcnt lgkmcnt(6)
	v_mfma_f32_16x16x32_bf16 v[8:11], v[120:123], v[156:159], v[8:11]
	ds_read_b128 v[90:93], v242 offset:34816
	s_waitcnt lgkmcnt(6)
	v_mfma_f32_16x16x32_bf16 v[12:15], v[120:123], v[160:163], v[12:15]
	ds_read_b128 v[112:115], v242 offset:36864
	s_waitcnt lgkmcnt(6)
	v_mfma_f32_16x16x32_bf16 v[16:19], v[124:127], v[140:143], v[16:19]
	ds_read_b128 v[252:255], v242 offset:38912
	v_mfma_f32_16x16x32_bf16 v[20:23], v[124:127], v[152:155], v[20:23]
	ds_read_b128 v[168:171], v240 offset:34816
	v_mfma_f32_16x16x32_bf16 v[24:27], v[124:127], v[156:159], v[24:27]
	ds_read_b128 v[244:247], v240 offset:36864
	v_mfma_f32_16x16x32_bf16 v[28:31], v[124:127], v[160:163], v[28:31]
	ds_read_b128 v[248:251], v240 offset:38912
	s_waitcnt lgkmcnt(9)
	v_mfma_f32_16x16x32_bf16 v[32:35], v[128:131], v[140:143], v[32:35]
	v_mfma_f32_16x16x32_bf16 v[36:39], v[128:131], v[152:155], v[36:39]
	v_mfma_f32_16x16x32_bf16 v[40:43], v[128:131], v[156:159], v[40:43]
	v_mfma_f32_16x16x32_bf16 v[44:47], v[128:131], v[160:163], v[44:47]
	s_waitcnt lgkmcnt(8)
	v_mfma_f32_16x16x32_bf16 v[48:51], v[132:135], v[140:143], v[48:51]
	v_mfma_f32_16x16x32_bf16 v[52:55], v[132:135], v[152:155], v[52:55]
	v_mfma_f32_16x16x32_bf16 v[56:59], v[132:135], v[156:159], v[56:59]
	v_mfma_f32_16x16x32_bf16 v[60:63], v[132:135], v[160:163], v[60:63]
	s_waitcnt lgkmcnt(6)
	v_mfma_f32_16x16x32_bf16 v[0:3], v[164:167], v[86:89], v[0:3]
	s_waitcnt vmcnt(8)
	ds_write_b128 v74, v[172:175]
	s_waitcnt lgkmcnt(6)
	v_mfma_f32_16x16x32_bf16 v[4:7], v[164:167], v[90:93], v[4:7]
	ds_write_b128 v74, v[176:179] offset:4096
	s_waitcnt lgkmcnt(6)
	v_mfma_f32_16x16x32_bf16 v[8:11], v[164:167], v[112:115], v[8:11]
	ds_write_b128 v74, v[180:183] offset:8192
	s_waitcnt lgkmcnt(6)
	v_mfma_f32_16x16x32_bf16 v[12:15], v[164:167], v[252:255], v[12:15]
	ds_write_b128 v74, v[184:187] offset:12288
	s_waitcnt lgkmcnt(6)
	v_mfma_f32_16x16x32_bf16 v[16:19], v[168:171], v[86:89], v[16:19]
	ds_write_b128 v74, v[188:191] offset:16384
	v_mfma_f32_16x16x32_bf16 v[20:23], v[168:171], v[90:93], v[20:23]
	ds_write_b128 v74, v[192:195] offset:20480
	v_mfma_f32_16x16x32_bf16 v[24:27], v[168:171], v[112:115], v[24:27]
	ds_write_b128 v74, v[196:199] offset:24576
	v_mfma_f32_16x16x32_bf16 v[28:31], v[168:171], v[252:255], v[28:31]
	ds_write_b128 v74, v[200:203] offset:28672
	s_waitcnt lgkmcnt(9)
	v_mfma_f32_16x16x32_bf16 v[32:35], v[244:247], v[86:89], v[32:35]
	global_load_dwordx4 v[172:175], v66, s[98:99] offset:512
	v_mfma_f32_16x16x32_bf16 v[36:39], v[244:247], v[90:93], v[36:39]
	global_load_dwordx4 v[176:179], v67, s[98:99] offset:512
	v_mfma_f32_16x16x32_bf16 v[40:43], v[244:247], v[112:115], v[40:43]
	global_load_dwordx4 v[180:183], v68, s[98:99] offset:512
	v_mfma_f32_16x16x32_bf16 v[44:47], v[244:247], v[252:255], v[44:47]
	global_load_dwordx4 v[184:187], v69, s[98:99] offset:512
	s_waitcnt lgkmcnt(8)
	v_mfma_f32_16x16x32_bf16 v[48:51], v[248:251], v[86:89], v[48:51]
	global_load_dwordx4 v[188:191], v66, s[100:101] offset:512
	v_mfma_f32_16x16x32_bf16 v[52:55], v[248:251], v[90:93], v[52:55]
	global_load_dwordx4 v[192:195], v67, s[100:101] offset:512
	v_mfma_f32_16x16x32_bf16 v[56:59], v[248:251], v[112:115], v[56:59]
	global_load_dwordx4 v[196:199], v68, s[100:101] offset:512
	v_mfma_f32_16x16x32_bf16 v[60:63], v[248:251], v[252:255], v[60:63]
	global_load_dwordx4 v[200:203], v69, s[100:101] offset:512
	s_waitcnt lgkmcnt(0)
	s_barrier
	ds_read_b128 v[120:123], v239
	ds_read_b128 v[140:143], v241
	ds_read_b128 v[152:155], v241 offset:2048
	ds_read_b128 v[156:159], v241 offset:4096
	ds_read_b128 v[160:163], v241 offset:6144
	ds_read_b128 v[124:127], v239 offset:2048
	ds_read_b128 v[128:131], v239 offset:4096
	ds_read_b128 v[132:135], v239 offset:6144
	s_waitcnt lgkmcnt(6)
	v_mfma_f32_16x16x32_bf16 v[0:3], v[120:123], v[140:143], v[0:3]
	ds_read_b128 v[164:167], v240
	s_waitcnt lgkmcnt(6)
	v_mfma_f32_16x16x32_bf16 v[4:7], v[120:123], v[152:155], v[4:7]
	ds_read_b128 v[86:89], v242
	s_waitcnt lgkmcnt(6)
	v_mfma_f32_16x16x32_bf16 v[8:11], v[120:123], v[156:159], v[8:11]
	ds_read_b128 v[90:93], v242 offset:2048
	s_waitcnt lgkmcnt(6)
	v_mfma_f32_16x16x32_bf16 v[12:15], v[120:123], v[160:163], v[12:15]
	ds_read_b128 v[112:115], v242 offset:4096
	s_waitcnt lgkmcnt(6)
	v_mfma_f32_16x16x32_bf16 v[16:19], v[124:127], v[140:143], v[16:19]
	ds_read_b128 v[252:255], v242 offset:6144
	v_mfma_f32_16x16x32_bf16 v[20:23], v[124:127], v[152:155], v[20:23]
	ds_read_b128 v[168:171], v240 offset:2048
	v_mfma_f32_16x16x32_bf16 v[24:27], v[124:127], v[156:159], v[24:27]
	ds_read_b128 v[244:247], v240 offset:4096
	v_mfma_f32_16x16x32_bf16 v[28:31], v[124:127], v[160:163], v[28:31]
	ds_read_b128 v[248:251], v240 offset:6144
	s_waitcnt lgkmcnt(9)
	v_mfma_f32_16x16x32_bf16 v[32:35], v[128:131], v[140:143], v[32:35]
	v_mfma_f32_16x16x32_bf16 v[36:39], v[128:131], v[152:155], v[36:39]
	v_mfma_f32_16x16x32_bf16 v[40:43], v[128:131], v[156:159], v[40:43]
	v_mfma_f32_16x16x32_bf16 v[44:47], v[128:131], v[160:163], v[44:47]
	s_waitcnt lgkmcnt(8)
	v_mfma_f32_16x16x32_bf16 v[48:51], v[132:135], v[140:143], v[48:51]
	v_mfma_f32_16x16x32_bf16 v[52:55], v[132:135], v[152:155], v[52:55]
	v_mfma_f32_16x16x32_bf16 v[56:59], v[132:135], v[156:159], v[56:59]
	v_mfma_f32_16x16x32_bf16 v[60:63], v[132:135], v[160:163], v[60:63]
	s_waitcnt lgkmcnt(6)
	v_mfma_f32_16x16x32_bf16 v[0:3], v[164:167], v[86:89], v[0:3]
	s_waitcnt vmcnt(8)
	ds_write_b128 v74, v[204:207] offset:32768
	s_waitcnt lgkmcnt(6)
	v_mfma_f32_16x16x32_bf16 v[4:7], v[164:167], v[90:93], v[4:7]
	ds_write_b128 v74, v[208:211] offset:36864
	s_waitcnt lgkmcnt(6)
	v_mfma_f32_16x16x32_bf16 v[8:11], v[164:167], v[112:115], v[8:11]
	ds_write_b128 v74, v[212:215] offset:40960
	s_waitcnt lgkmcnt(6)
	v_mfma_f32_16x16x32_bf16 v[12:15], v[164:167], v[252:255], v[12:15]
	ds_write_b128 v74, v[216:219] offset:45056
	s_waitcnt lgkmcnt(6)
	v_mfma_f32_16x16x32_bf16 v[16:19], v[168:171], v[86:89], v[16:19]
	ds_write_b128 v74, v[220:223] offset:49152
	v_mfma_f32_16x16x32_bf16 v[20:23], v[168:171], v[90:93], v[20:23]
	ds_write_b128 v74, v[224:227] offset:53248
	v_mfma_f32_16x16x32_bf16 v[24:27], v[168:171], v[112:115], v[24:27]
	ds_write_b128 v74, v[228:231] offset:57344
	v_mfma_f32_16x16x32_bf16 v[28:31], v[168:171], v[252:255], v[28:31]
	ds_write_b128 v74, v[232:235] offset:61440
	s_waitcnt lgkmcnt(9)
	v_mfma_f32_16x16x32_bf16 v[32:35], v[244:247], v[86:89], v[32:35]
	global_load_dwordx4 v[204:207], v66, s[98:99] offset:640
	v_mfma_f32_16x16x32_bf16 v[36:39], v[244:247], v[90:93], v[36:39]
	global_load_dwordx4 v[208:211], v67, s[98:99] offset:640
	v_mfma_f32_16x16x32_bf16 v[40:43], v[244:247], v[112:115], v[40:43]
	global_load_dwordx4 v[212:215], v68, s[98:99] offset:640
	v_mfma_f32_16x16x32_bf16 v[44:47], v[244:247], v[252:255], v[44:47]
	global_load_dwordx4 v[216:219], v69, s[98:99] offset:640
	s_waitcnt lgkmcnt(8)
	v_mfma_f32_16x16x32_bf16 v[48:51], v[248:251], v[86:89], v[48:51]
	global_load_dwordx4 v[220:223], v66, s[100:101] offset:640
	v_mfma_f32_16x16x32_bf16 v[52:55], v[248:251], v[90:93], v[52:55]
	global_load_dwordx4 v[224:227], v67, s[100:101] offset:640
	v_mfma_f32_16x16x32_bf16 v[56:59], v[248:251], v[112:115], v[56:59]
	global_load_dwordx4 v[228:231], v68, s[100:101] offset:640
	v_mfma_f32_16x16x32_bf16 v[60:63], v[248:251], v[252:255], v[60:63]
	global_load_dwordx4 v[232:235], v69, s[100:101] offset:640
	s_waitcnt lgkmcnt(0)
	s_barrier
	ds_read_b128 v[120:123], v239 offset:32768
	ds_read_b128 v[140:143], v241 offset:32768
	ds_read_b128 v[152:155], v241 offset:34816
	ds_read_b128 v[156:159], v241 offset:36864
	ds_read_b128 v[160:163], v241 offset:38912
	ds_read_b128 v[124:127], v239 offset:34816
	ds_read_b128 v[128:131], v239 offset:36864
	ds_read_b128 v[132:135], v239 offset:38912
	s_waitcnt lgkmcnt(6)
	v_mfma_f32_16x16x32_bf16 v[0:3], v[120:123], v[140:143], v[0:3]
	ds_read_b128 v[164:167], v240 offset:32768
	s_waitcnt lgkmcnt(6)
	v_mfma_f32_16x16x32_bf16 v[4:7], v[120:123], v[152:155], v[4:7]
	ds_read_b128 v[86:89], v242 offset:32768
	s_waitcnt lgkmcnt(6)
	v_mfma_f32_16x16x32_bf16 v[8:11], v[120:123], v[156:159], v[8:11]
	ds_read_b128 v[90:93], v242 offset:34816
	s_waitcnt lgkmcnt(6)
	v_mfma_f32_16x16x32_bf16 v[12:15], v[120:123], v[160:163], v[12:15]
	ds_read_b128 v[112:115], v242 offset:36864
	s_waitcnt lgkmcnt(6)
	v_mfma_f32_16x16x32_bf16 v[16:19], v[124:127], v[140:143], v[16:19]
	ds_read_b128 v[252:255], v242 offset:38912
	v_mfma_f32_16x16x32_bf16 v[20:23], v[124:127], v[152:155], v[20:23]
	ds_read_b128 v[168:171], v240 offset:34816
	v_mfma_f32_16x16x32_bf16 v[24:27], v[124:127], v[156:159], v[24:27]
	ds_read_b128 v[244:247], v240 offset:36864
	v_mfma_f32_16x16x32_bf16 v[28:31], v[124:127], v[160:163], v[28:31]
	ds_read_b128 v[248:251], v240 offset:38912
	s_waitcnt lgkmcnt(9)
	v_mfma_f32_16x16x32_bf16 v[32:35], v[128:131], v[140:143], v[32:35]
	v_mfma_f32_16x16x32_bf16 v[36:39], v[128:131], v[152:155], v[36:39]
	v_mfma_f32_16x16x32_bf16 v[40:43], v[128:131], v[156:159], v[40:43]
	v_mfma_f32_16x16x32_bf16 v[44:47], v[128:131], v[160:163], v[44:47]
	s_waitcnt lgkmcnt(8)
	v_mfma_f32_16x16x32_bf16 v[48:51], v[132:135], v[140:143], v[48:51]
	v_mfma_f32_16x16x32_bf16 v[52:55], v[132:135], v[152:155], v[52:55]
	v_mfma_f32_16x16x32_bf16 v[56:59], v[132:135], v[156:159], v[56:59]
	v_mfma_f32_16x16x32_bf16 v[60:63], v[132:135], v[160:163], v[60:63]
	s_waitcnt lgkmcnt(6)
	v_mfma_f32_16x16x32_bf16 v[0:3], v[164:167], v[86:89], v[0:3]
	s_waitcnt vmcnt(8)
	ds_write_b128 v74, v[172:175]
	s_waitcnt lgkmcnt(6)
	v_mfma_f32_16x16x32_bf16 v[4:7], v[164:167], v[90:93], v[4:7]
	ds_write_b128 v74, v[176:179] offset:4096
	s_waitcnt lgkmcnt(6)
	v_mfma_f32_16x16x32_bf16 v[8:11], v[164:167], v[112:115], v[8:11]
	ds_write_b128 v74, v[180:183] offset:8192
	s_waitcnt lgkmcnt(6)
	v_mfma_f32_16x16x32_bf16 v[12:15], v[164:167], v[252:255], v[12:15]
	ds_write_b128 v74, v[184:187] offset:12288
	s_waitcnt lgkmcnt(6)
	v_mfma_f32_16x16x32_bf16 v[16:19], v[168:171], v[86:89], v[16:19]
	ds_write_b128 v74, v[188:191] offset:16384
	v_mfma_f32_16x16x32_bf16 v[20:23], v[168:171], v[90:93], v[20:23]
	ds_write_b128 v74, v[192:195] offset:20480
	v_mfma_f32_16x16x32_bf16 v[24:27], v[168:171], v[112:115], v[24:27]
	ds_write_b128 v74, v[196:199] offset:24576
	v_mfma_f32_16x16x32_bf16 v[28:31], v[168:171], v[252:255], v[28:31]
	ds_write_b128 v74, v[200:203] offset:28672
	s_waitcnt lgkmcnt(9)
	v_mfma_f32_16x16x32_bf16 v[32:35], v[244:247], v[86:89], v[32:35]
	global_load_dwordx4 v[172:175], v66, s[98:99] offset:768
	v_mfma_f32_16x16x32_bf16 v[36:39], v[244:247], v[90:93], v[36:39]
	global_load_dwordx4 v[176:179], v67, s[98:99] offset:768
	v_mfma_f32_16x16x32_bf16 v[40:43], v[244:247], v[112:115], v[40:43]
	global_load_dwordx4 v[180:183], v68, s[98:99] offset:768
	v_mfma_f32_16x16x32_bf16 v[44:47], v[244:247], v[252:255], v[44:47]
	global_load_dwordx4 v[184:187], v69, s[98:99] offset:768
	s_waitcnt lgkmcnt(8)
	v_mfma_f32_16x16x32_bf16 v[48:51], v[248:251], v[86:89], v[48:51]
	global_load_dwordx4 v[188:191], v66, s[100:101] offset:768
	v_mfma_f32_16x16x32_bf16 v[52:55], v[248:251], v[90:93], v[52:55]
	global_load_dwordx4 v[192:195], v67, s[100:101] offset:768
	v_mfma_f32_16x16x32_bf16 v[56:59], v[248:251], v[112:115], v[56:59]
	global_load_dwordx4 v[196:199], v68, s[100:101] offset:768
	v_mfma_f32_16x16x32_bf16 v[60:63], v[248:251], v[252:255], v[60:63]
	global_load_dwordx4 v[200:203], v69, s[100:101] offset:768
	s_waitcnt lgkmcnt(0)
	s_barrier
	ds_read_b128 v[120:123], v239
	ds_read_b128 v[140:143], v241
	ds_read_b128 v[152:155], v241 offset:2048
	ds_read_b128 v[156:159], v241 offset:4096
	ds_read_b128 v[160:163], v241 offset:6144
	ds_read_b128 v[124:127], v239 offset:2048
	ds_read_b128 v[128:131], v239 offset:4096
	ds_read_b128 v[132:135], v239 offset:6144
	s_waitcnt lgkmcnt(6)
	v_mfma_f32_16x16x32_bf16 v[0:3], v[120:123], v[140:143], v[0:3]
	ds_read_b128 v[164:167], v240
	s_waitcnt lgkmcnt(6)
	v_mfma_f32_16x16x32_bf16 v[4:7], v[120:123], v[152:155], v[4:7]
	ds_read_b128 v[86:89], v242
	s_waitcnt lgkmcnt(6)
	v_mfma_f32_16x16x32_bf16 v[8:11], v[120:123], v[156:159], v[8:11]
	ds_read_b128 v[90:93], v242 offset:2048
	s_waitcnt lgkmcnt(6)
	v_mfma_f32_16x16x32_bf16 v[12:15], v[120:123], v[160:163], v[12:15]
	ds_read_b128 v[112:115], v242 offset:4096
	s_waitcnt lgkmcnt(6)
	v_mfma_f32_16x16x32_bf16 v[16:19], v[124:127], v[140:143], v[16:19]
	ds_read_b128 v[252:255], v242 offset:6144
	v_mfma_f32_16x16x32_bf16 v[20:23], v[124:127], v[152:155], v[20:23]
	ds_read_b128 v[168:171], v240 offset:2048
	v_mfma_f32_16x16x32_bf16 v[24:27], v[124:127], v[156:159], v[24:27]
	ds_read_b128 v[244:247], v240 offset:4096
	v_mfma_f32_16x16x32_bf16 v[28:31], v[124:127], v[160:163], v[28:31]
	ds_read_b128 v[248:251], v240 offset:6144
	s_waitcnt lgkmcnt(9)
	v_mfma_f32_16x16x32_bf16 v[32:35], v[128:131], v[140:143], v[32:35]
	v_mfma_f32_16x16x32_bf16 v[36:39], v[128:131], v[152:155], v[36:39]
	v_mfma_f32_16x16x32_bf16 v[40:43], v[128:131], v[156:159], v[40:43]
	v_mfma_f32_16x16x32_bf16 v[44:47], v[128:131], v[160:163], v[44:47]
	s_waitcnt lgkmcnt(8)
	v_mfma_f32_16x16x32_bf16 v[48:51], v[132:135], v[140:143], v[48:51]
	v_mfma_f32_16x16x32_bf16 v[52:55], v[132:135], v[152:155], v[52:55]
	v_mfma_f32_16x16x32_bf16 v[56:59], v[132:135], v[156:159], v[56:59]
	v_mfma_f32_16x16x32_bf16 v[60:63], v[132:135], v[160:163], v[60:63]
	s_waitcnt lgkmcnt(6)
	v_mfma_f32_16x16x32_bf16 v[0:3], v[164:167], v[86:89], v[0:3]
	s_waitcnt vmcnt(8)
	ds_write_b128 v74, v[204:207] offset:32768
	s_waitcnt lgkmcnt(6)
	v_mfma_f32_16x16x32_bf16 v[4:7], v[164:167], v[90:93], v[4:7]
	ds_write_b128 v74, v[208:211] offset:36864
	s_waitcnt lgkmcnt(6)
	v_mfma_f32_16x16x32_bf16 v[8:11], v[164:167], v[112:115], v[8:11]
	ds_write_b128 v74, v[212:215] offset:40960
	s_waitcnt lgkmcnt(6)
	v_mfma_f32_16x16x32_bf16 v[12:15], v[164:167], v[252:255], v[12:15]
	ds_write_b128 v74, v[216:219] offset:45056
	s_waitcnt lgkmcnt(6)
	v_mfma_f32_16x16x32_bf16 v[16:19], v[168:171], v[86:89], v[16:19]
	ds_write_b128 v74, v[220:223] offset:49152
	v_mfma_f32_16x16x32_bf16 v[20:23], v[168:171], v[90:93], v[20:23]
	ds_write_b128 v74, v[224:227] offset:53248
	v_mfma_f32_16x16x32_bf16 v[24:27], v[168:171], v[112:115], v[24:27]
	ds_write_b128 v74, v[228:231] offset:57344
	v_mfma_f32_16x16x32_bf16 v[28:31], v[168:171], v[252:255], v[28:31]
	ds_write_b128 v74, v[232:235] offset:61440
	s_waitcnt lgkmcnt(9)
	v_mfma_f32_16x16x32_bf16 v[32:35], v[244:247], v[86:89], v[32:35]
	global_load_dwordx4 v[204:207], v66, s[98:99] offset:896
	v_mfma_f32_16x16x32_bf16 v[36:39], v[244:247], v[90:93], v[36:39]
	global_load_dwordx4 v[208:211], v67, s[98:99] offset:896
	v_mfma_f32_16x16x32_bf16 v[40:43], v[244:247], v[112:115], v[40:43]
	global_load_dwordx4 v[212:215], v68, s[98:99] offset:896
	v_mfma_f32_16x16x32_bf16 v[44:47], v[244:247], v[252:255], v[44:47]
	global_load_dwordx4 v[216:219], v69, s[98:99] offset:896
	s_waitcnt lgkmcnt(8)
	v_mfma_f32_16x16x32_bf16 v[48:51], v[248:251], v[86:89], v[48:51]
	global_load_dwordx4 v[220:223], v66, s[100:101] offset:896
	v_mfma_f32_16x16x32_bf16 v[52:55], v[248:251], v[90:93], v[52:55]
	global_load_dwordx4 v[224:227], v67, s[100:101] offset:896
	v_mfma_f32_16x16x32_bf16 v[56:59], v[248:251], v[112:115], v[56:59]
	global_load_dwordx4 v[228:231], v68, s[100:101] offset:896
	v_mfma_f32_16x16x32_bf16 v[60:63], v[248:251], v[252:255], v[60:63]
	global_load_dwordx4 v[232:235], v69, s[100:101] offset:896
	s_waitcnt lgkmcnt(0)
	s_barrier
	ds_read_b128 v[120:123], v239 offset:32768
	ds_read_b128 v[140:143], v241 offset:32768
	ds_read_b128 v[152:155], v241 offset:34816
	ds_read_b128 v[156:159], v241 offset:36864
	ds_read_b128 v[160:163], v241 offset:38912
	ds_read_b128 v[124:127], v239 offset:34816
	ds_read_b128 v[128:131], v239 offset:36864
	ds_read_b128 v[132:135], v239 offset:38912
	s_waitcnt lgkmcnt(6)
	v_mfma_f32_16x16x32_bf16 v[0:3], v[120:123], v[140:143], v[0:3]
	ds_read_b128 v[164:167], v240 offset:32768
	s_waitcnt lgkmcnt(6)
	v_mfma_f32_16x16x32_bf16 v[4:7], v[120:123], v[152:155], v[4:7]
	ds_read_b128 v[86:89], v242 offset:32768
	s_waitcnt lgkmcnt(6)
	v_mfma_f32_16x16x32_bf16 v[8:11], v[120:123], v[156:159], v[8:11]
	ds_read_b128 v[90:93], v242 offset:34816
	s_waitcnt lgkmcnt(6)
	v_mfma_f32_16x16x32_bf16 v[12:15], v[120:123], v[160:163], v[12:15]
	ds_read_b128 v[112:115], v242 offset:36864
	s_waitcnt lgkmcnt(6)
	v_mfma_f32_16x16x32_bf16 v[16:19], v[124:127], v[140:143], v[16:19]
	ds_read_b128 v[252:255], v242 offset:38912
	v_mfma_f32_16x16x32_bf16 v[20:23], v[124:127], v[152:155], v[20:23]
	ds_read_b128 v[168:171], v240 offset:34816
	v_mfma_f32_16x16x32_bf16 v[24:27], v[124:127], v[156:159], v[24:27]
	ds_read_b128 v[244:247], v240 offset:36864
	v_mfma_f32_16x16x32_bf16 v[28:31], v[124:127], v[160:163], v[28:31]
	ds_read_b128 v[248:251], v240 offset:38912
	s_waitcnt lgkmcnt(9)
	v_mfma_f32_16x16x32_bf16 v[32:35], v[128:131], v[140:143], v[32:35]
	v_mfma_f32_16x16x32_bf16 v[36:39], v[128:131], v[152:155], v[36:39]
	v_mfma_f32_16x16x32_bf16 v[40:43], v[128:131], v[156:159], v[40:43]
	v_mfma_f32_16x16x32_bf16 v[44:47], v[128:131], v[160:163], v[44:47]
	s_waitcnt lgkmcnt(8)
	v_mfma_f32_16x16x32_bf16 v[48:51], v[132:135], v[140:143], v[48:51]
	v_mfma_f32_16x16x32_bf16 v[52:55], v[132:135], v[152:155], v[52:55]
	v_mfma_f32_16x16x32_bf16 v[56:59], v[132:135], v[156:159], v[56:59]
	v_mfma_f32_16x16x32_bf16 v[60:63], v[132:135], v[160:163], v[60:63]
	s_waitcnt lgkmcnt(6)
	v_mfma_f32_16x16x32_bf16 v[0:3], v[164:167], v[86:89], v[0:3]
	s_waitcnt vmcnt(8)
	ds_write_b128 v74, v[172:175]
	s_waitcnt lgkmcnt(6)
	v_mfma_f32_16x16x32_bf16 v[4:7], v[164:167], v[90:93], v[4:7]
	ds_write_b128 v74, v[176:179] offset:4096
	s_waitcnt lgkmcnt(6)
	v_mfma_f32_16x16x32_bf16 v[8:11], v[164:167], v[112:115], v[8:11]
	ds_write_b128 v74, v[180:183] offset:8192
	s_waitcnt lgkmcnt(6)
	v_mfma_f32_16x16x32_bf16 v[12:15], v[164:167], v[252:255], v[12:15]
	ds_write_b128 v74, v[184:187] offset:12288
	s_waitcnt lgkmcnt(6)
	v_mfma_f32_16x16x32_bf16 v[16:19], v[168:171], v[86:89], v[16:19]
	ds_write_b128 v74, v[188:191] offset:16384
	v_mfma_f32_16x16x32_bf16 v[20:23], v[168:171], v[90:93], v[20:23]
	ds_write_b128 v74, v[192:195] offset:20480
	v_mfma_f32_16x16x32_bf16 v[24:27], v[168:171], v[112:115], v[24:27]
	ds_write_b128 v74, v[196:199] offset:24576
	v_mfma_f32_16x16x32_bf16 v[28:31], v[168:171], v[252:255], v[28:31]
	ds_write_b128 v74, v[200:203] offset:28672
	s_waitcnt lgkmcnt(9)
	v_mfma_f32_16x16x32_bf16 v[32:35], v[244:247], v[86:89], v[32:35]
	global_load_dwordx4 v[172:175], v66, s[98:99] offset:1024
	v_mfma_f32_16x16x32_bf16 v[36:39], v[244:247], v[90:93], v[36:39]
	global_load_dwordx4 v[176:179], v67, s[98:99] offset:1024
	v_mfma_f32_16x16x32_bf16 v[40:43], v[244:247], v[112:115], v[40:43]
	global_load_dwordx4 v[180:183], v68, s[98:99] offset:1024
	v_mfma_f32_16x16x32_bf16 v[44:47], v[244:247], v[252:255], v[44:47]
	global_load_dwordx4 v[184:187], v69, s[98:99] offset:1024
	s_waitcnt lgkmcnt(8)
	v_mfma_f32_16x16x32_bf16 v[48:51], v[248:251], v[86:89], v[48:51]
	global_load_dwordx4 v[188:191], v66, s[100:101] offset:1024
	v_mfma_f32_16x16x32_bf16 v[52:55], v[248:251], v[90:93], v[52:55]
	global_load_dwordx4 v[192:195], v67, s[100:101] offset:1024
	v_mfma_f32_16x16x32_bf16 v[56:59], v[248:251], v[112:115], v[56:59]
	global_load_dwordx4 v[196:199], v68, s[100:101] offset:1024
	v_mfma_f32_16x16x32_bf16 v[60:63], v[248:251], v[252:255], v[60:63]
	global_load_dwordx4 v[200:203], v69, s[100:101] offset:1024
	s_waitcnt lgkmcnt(0)
	s_barrier
	ds_read_b128 v[120:123], v239
	ds_read_b128 v[140:143], v241
	ds_read_b128 v[152:155], v241 offset:2048
	ds_read_b128 v[156:159], v241 offset:4096
	ds_read_b128 v[160:163], v241 offset:6144
	ds_read_b128 v[124:127], v239 offset:2048
	ds_read_b128 v[128:131], v239 offset:4096
	ds_read_b128 v[132:135], v239 offset:6144
	s_waitcnt lgkmcnt(6)
	v_mfma_f32_16x16x32_bf16 v[0:3], v[120:123], v[140:143], v[0:3]
	ds_read_b128 v[164:167], v240
	s_waitcnt lgkmcnt(6)
	v_mfma_f32_16x16x32_bf16 v[4:7], v[120:123], v[152:155], v[4:7]
	ds_read_b128 v[86:89], v242
	s_waitcnt lgkmcnt(6)
	v_mfma_f32_16x16x32_bf16 v[8:11], v[120:123], v[156:159], v[8:11]
	ds_read_b128 v[90:93], v242 offset:2048
	s_waitcnt lgkmcnt(6)
	v_mfma_f32_16x16x32_bf16 v[12:15], v[120:123], v[160:163], v[12:15]
	ds_read_b128 v[112:115], v242 offset:4096
	s_waitcnt lgkmcnt(6)
	v_mfma_f32_16x16x32_bf16 v[16:19], v[124:127], v[140:143], v[16:19]
	ds_read_b128 v[252:255], v242 offset:6144
	v_mfma_f32_16x16x32_bf16 v[20:23], v[124:127], v[152:155], v[20:23]
	ds_read_b128 v[168:171], v240 offset:2048
	v_mfma_f32_16x16x32_bf16 v[24:27], v[124:127], v[156:159], v[24:27]
	ds_read_b128 v[244:247], v240 offset:4096
	v_mfma_f32_16x16x32_bf16 v[28:31], v[124:127], v[160:163], v[28:31]
	ds_read_b128 v[248:251], v240 offset:6144
	s_waitcnt lgkmcnt(9)
	v_mfma_f32_16x16x32_bf16 v[32:35], v[128:131], v[140:143], v[32:35]
	v_mfma_f32_16x16x32_bf16 v[36:39], v[128:131], v[152:155], v[36:39]
	v_mfma_f32_16x16x32_bf16 v[40:43], v[128:131], v[156:159], v[40:43]
	v_mfma_f32_16x16x32_bf16 v[44:47], v[128:131], v[160:163], v[44:47]
	s_waitcnt lgkmcnt(8)
	v_mfma_f32_16x16x32_bf16 v[48:51], v[132:135], v[140:143], v[48:51]
	v_mfma_f32_16x16x32_bf16 v[52:55], v[132:135], v[152:155], v[52:55]
	v_mfma_f32_16x16x32_bf16 v[56:59], v[132:135], v[156:159], v[56:59]
	v_mfma_f32_16x16x32_bf16 v[60:63], v[132:135], v[160:163], v[60:63]
	s_waitcnt lgkmcnt(6)
	v_mfma_f32_16x16x32_bf16 v[0:3], v[164:167], v[86:89], v[0:3]
	s_waitcnt vmcnt(8)
	ds_write_b128 v74, v[204:207] offset:32768
	s_waitcnt lgkmcnt(6)
	v_mfma_f32_16x16x32_bf16 v[4:7], v[164:167], v[90:93], v[4:7]
	ds_write_b128 v74, v[208:211] offset:36864
	s_waitcnt lgkmcnt(6)
	v_mfma_f32_16x16x32_bf16 v[8:11], v[164:167], v[112:115], v[8:11]
	ds_write_b128 v74, v[212:215] offset:40960
	s_waitcnt lgkmcnt(6)
	v_mfma_f32_16x16x32_bf16 v[12:15], v[164:167], v[252:255], v[12:15]
	ds_write_b128 v74, v[216:219] offset:45056
	s_waitcnt lgkmcnt(6)
	v_mfma_f32_16x16x32_bf16 v[16:19], v[168:171], v[86:89], v[16:19]
	ds_write_b128 v74, v[220:223] offset:49152
	v_mfma_f32_16x16x32_bf16 v[20:23], v[168:171], v[90:93], v[20:23]
	ds_write_b128 v74, v[224:227] offset:53248
	v_mfma_f32_16x16x32_bf16 v[24:27], v[168:171], v[112:115], v[24:27]
	ds_write_b128 v74, v[228:231] offset:57344
	v_mfma_f32_16x16x32_bf16 v[28:31], v[168:171], v[252:255], v[28:31]
	ds_write_b128 v74, v[232:235] offset:61440
	s_waitcnt lgkmcnt(9)
	v_mfma_f32_16x16x32_bf16 v[32:35], v[244:247], v[86:89], v[32:35]
	global_load_dwordx4 v[204:207], v66, s[98:99] offset:1152
	v_mfma_f32_16x16x32_bf16 v[36:39], v[244:247], v[90:93], v[36:39]
	global_load_dwordx4 v[208:211], v67, s[98:99] offset:1152
	v_mfma_f32_16x16x32_bf16 v[40:43], v[244:247], v[112:115], v[40:43]
	global_load_dwordx4 v[212:215], v68, s[98:99] offset:1152
	v_mfma_f32_16x16x32_bf16 v[44:47], v[244:247], v[252:255], v[44:47]
	global_load_dwordx4 v[216:219], v69, s[98:99] offset:1152
	s_waitcnt lgkmcnt(8)
	v_mfma_f32_16x16x32_bf16 v[48:51], v[248:251], v[86:89], v[48:51]
	global_load_dwordx4 v[220:223], v66, s[100:101] offset:1152
	v_mfma_f32_16x16x32_bf16 v[52:55], v[248:251], v[90:93], v[52:55]
	global_load_dwordx4 v[224:227], v67, s[100:101] offset:1152
	v_mfma_f32_16x16x32_bf16 v[56:59], v[248:251], v[112:115], v[56:59]
	global_load_dwordx4 v[228:231], v68, s[100:101] offset:1152
	v_mfma_f32_16x16x32_bf16 v[60:63], v[248:251], v[252:255], v[60:63]
	global_load_dwordx4 v[232:235], v69, s[100:101] offset:1152
	s_waitcnt lgkmcnt(0)
	s_barrier
	ds_read_b128 v[120:123], v239 offset:32768
	ds_read_b128 v[140:143], v241 offset:32768
	ds_read_b128 v[152:155], v241 offset:34816
	ds_read_b128 v[156:159], v241 offset:36864
	ds_read_b128 v[160:163], v241 offset:38912
	ds_read_b128 v[124:127], v239 offset:34816
	ds_read_b128 v[128:131], v239 offset:36864
	ds_read_b128 v[132:135], v239 offset:38912
	s_waitcnt lgkmcnt(6)
	v_mfma_f32_16x16x32_bf16 v[0:3], v[120:123], v[140:143], v[0:3]
	ds_read_b128 v[164:167], v240 offset:32768
	s_waitcnt lgkmcnt(6)
	v_mfma_f32_16x16x32_bf16 v[4:7], v[120:123], v[152:155], v[4:7]
	ds_read_b128 v[86:89], v242 offset:32768
	s_waitcnt lgkmcnt(6)
	v_mfma_f32_16x16x32_bf16 v[8:11], v[120:123], v[156:159], v[8:11]
	ds_read_b128 v[90:93], v242 offset:34816
	s_waitcnt lgkmcnt(6)
	v_mfma_f32_16x16x32_bf16 v[12:15], v[120:123], v[160:163], v[12:15]
	ds_read_b128 v[112:115], v242 offset:36864
	s_waitcnt lgkmcnt(6)
	v_mfma_f32_16x16x32_bf16 v[16:19], v[124:127], v[140:143], v[16:19]
	ds_read_b128 v[252:255], v242 offset:38912
	v_mfma_f32_16x16x32_bf16 v[20:23], v[124:127], v[152:155], v[20:23]
	ds_read_b128 v[168:171], v240 offset:34816
	v_mfma_f32_16x16x32_bf16 v[24:27], v[124:127], v[156:159], v[24:27]
	ds_read_b128 v[244:247], v240 offset:36864
	v_mfma_f32_16x16x32_bf16 v[28:31], v[124:127], v[160:163], v[28:31]
	ds_read_b128 v[248:251], v240 offset:38912
	s_waitcnt lgkmcnt(9)
	v_mfma_f32_16x16x32_bf16 v[32:35], v[128:131], v[140:143], v[32:35]
	v_mfma_f32_16x16x32_bf16 v[36:39], v[128:131], v[152:155], v[36:39]
	v_mfma_f32_16x16x32_bf16 v[40:43], v[128:131], v[156:159], v[40:43]
	v_mfma_f32_16x16x32_bf16 v[44:47], v[128:131], v[160:163], v[44:47]
	s_waitcnt lgkmcnt(8)
	v_mfma_f32_16x16x32_bf16 v[48:51], v[132:135], v[140:143], v[48:51]
	v_mfma_f32_16x16x32_bf16 v[52:55], v[132:135], v[152:155], v[52:55]
	v_mfma_f32_16x16x32_bf16 v[56:59], v[132:135], v[156:159], v[56:59]
	v_mfma_f32_16x16x32_bf16 v[60:63], v[132:135], v[160:163], v[60:63]
	s_waitcnt lgkmcnt(6)
	v_mfma_f32_16x16x32_bf16 v[0:3], v[164:167], v[86:89], v[0:3]
	s_waitcnt vmcnt(8)
	ds_write_b128 v74, v[172:175]
	s_waitcnt lgkmcnt(6)
	v_mfma_f32_16x16x32_bf16 v[4:7], v[164:167], v[90:93], v[4:7]
	ds_write_b128 v74, v[176:179] offset:4096
	s_waitcnt lgkmcnt(6)
	v_mfma_f32_16x16x32_bf16 v[8:11], v[164:167], v[112:115], v[8:11]
	ds_write_b128 v74, v[180:183] offset:8192
	s_waitcnt lgkmcnt(6)
	v_mfma_f32_16x16x32_bf16 v[12:15], v[164:167], v[252:255], v[12:15]
	ds_write_b128 v74, v[184:187] offset:12288
	s_waitcnt lgkmcnt(6)
	v_mfma_f32_16x16x32_bf16 v[16:19], v[168:171], v[86:89], v[16:19]
	ds_write_b128 v74, v[188:191] offset:16384
	v_mfma_f32_16x16x32_bf16 v[20:23], v[168:171], v[90:93], v[20:23]
	ds_write_b128 v74, v[192:195] offset:20480
	v_mfma_f32_16x16x32_bf16 v[24:27], v[168:171], v[112:115], v[24:27]
	ds_write_b128 v74, v[196:199] offset:24576
	v_mfma_f32_16x16x32_bf16 v[28:31], v[168:171], v[252:255], v[28:31]
	ds_write_b128 v74, v[200:203] offset:28672
	s_waitcnt lgkmcnt(9)
	v_mfma_f32_16x16x32_bf16 v[32:35], v[244:247], v[86:89], v[32:35]
	global_load_dwordx4 v[172:175], v66, s[98:99] offset:1280
	v_mfma_f32_16x16x32_bf16 v[36:39], v[244:247], v[90:93], v[36:39]
	global_load_dwordx4 v[176:179], v67, s[98:99] offset:1280
	v_mfma_f32_16x16x32_bf16 v[40:43], v[244:247], v[112:115], v[40:43]
	global_load_dwordx4 v[180:183], v68, s[98:99] offset:1280
	v_mfma_f32_16x16x32_bf16 v[44:47], v[244:247], v[252:255], v[44:47]
	global_load_dwordx4 v[184:187], v69, s[98:99] offset:1280
	s_waitcnt lgkmcnt(8)
	v_mfma_f32_16x16x32_bf16 v[48:51], v[248:251], v[86:89], v[48:51]
	global_load_dwordx4 v[188:191], v66, s[100:101] offset:1280
	v_mfma_f32_16x16x32_bf16 v[52:55], v[248:251], v[90:93], v[52:55]
	global_load_dwordx4 v[192:195], v67, s[100:101] offset:1280
	v_mfma_f32_16x16x32_bf16 v[56:59], v[248:251], v[112:115], v[56:59]
	global_load_dwordx4 v[196:199], v68, s[100:101] offset:1280
	v_mfma_f32_16x16x32_bf16 v[60:63], v[248:251], v[252:255], v[60:63]
	global_load_dwordx4 v[200:203], v69, s[100:101] offset:1280
	s_waitcnt lgkmcnt(0)
	s_barrier
	ds_read_b128 v[120:123], v239
	ds_read_b128 v[140:143], v241
	ds_read_b128 v[152:155], v241 offset:2048
	ds_read_b128 v[156:159], v241 offset:4096
	ds_read_b128 v[160:163], v241 offset:6144
	ds_read_b128 v[124:127], v239 offset:2048
	ds_read_b128 v[128:131], v239 offset:4096
	ds_read_b128 v[132:135], v239 offset:6144
	s_waitcnt lgkmcnt(6)
	v_mfma_f32_16x16x32_bf16 v[0:3], v[120:123], v[140:143], v[0:3]
	ds_read_b128 v[164:167], v240
	s_waitcnt lgkmcnt(6)
	v_mfma_f32_16x16x32_bf16 v[4:7], v[120:123], v[152:155], v[4:7]
	ds_read_b128 v[86:89], v242
	s_waitcnt lgkmcnt(6)
	v_mfma_f32_16x16x32_bf16 v[8:11], v[120:123], v[156:159], v[8:11]
	ds_read_b128 v[90:93], v242 offset:2048
	s_waitcnt lgkmcnt(6)
	v_mfma_f32_16x16x32_bf16 v[12:15], v[120:123], v[160:163], v[12:15]
	ds_read_b128 v[112:115], v242 offset:4096
	s_waitcnt lgkmcnt(6)
	v_mfma_f32_16x16x32_bf16 v[16:19], v[124:127], v[140:143], v[16:19]
	ds_read_b128 v[252:255], v242 offset:6144
	v_mfma_f32_16x16x32_bf16 v[20:23], v[124:127], v[152:155], v[20:23]
	ds_read_b128 v[168:171], v240 offset:2048
	v_mfma_f32_16x16x32_bf16 v[24:27], v[124:127], v[156:159], v[24:27]
	ds_read_b128 v[244:247], v240 offset:4096
	v_mfma_f32_16x16x32_bf16 v[28:31], v[124:127], v[160:163], v[28:31]
	ds_read_b128 v[248:251], v240 offset:6144
	s_waitcnt lgkmcnt(9)
	v_mfma_f32_16x16x32_bf16 v[32:35], v[128:131], v[140:143], v[32:35]
	v_mfma_f32_16x16x32_bf16 v[36:39], v[128:131], v[152:155], v[36:39]
	v_mfma_f32_16x16x32_bf16 v[40:43], v[128:131], v[156:159], v[40:43]
	v_mfma_f32_16x16x32_bf16 v[44:47], v[128:131], v[160:163], v[44:47]
	s_waitcnt lgkmcnt(8)
	v_mfma_f32_16x16x32_bf16 v[48:51], v[132:135], v[140:143], v[48:51]
	v_mfma_f32_16x16x32_bf16 v[52:55], v[132:135], v[152:155], v[52:55]
	v_mfma_f32_16x16x32_bf16 v[56:59], v[132:135], v[156:159], v[56:59]
	v_mfma_f32_16x16x32_bf16 v[60:63], v[132:135], v[160:163], v[60:63]
	s_waitcnt lgkmcnt(6)
	v_mfma_f32_16x16x32_bf16 v[0:3], v[164:167], v[86:89], v[0:3]
	s_waitcnt vmcnt(8)
	ds_write_b128 v74, v[204:207] offset:32768
	s_waitcnt lgkmcnt(6)
	v_mfma_f32_16x16x32_bf16 v[4:7], v[164:167], v[90:93], v[4:7]
	ds_write_b128 v74, v[208:211] offset:36864
	s_waitcnt lgkmcnt(6)
	v_mfma_f32_16x16x32_bf16 v[8:11], v[164:167], v[112:115], v[8:11]
	ds_write_b128 v74, v[212:215] offset:40960
	s_waitcnt lgkmcnt(6)
	v_mfma_f32_16x16x32_bf16 v[12:15], v[164:167], v[252:255], v[12:15]
	ds_write_b128 v74, v[216:219] offset:45056
	s_waitcnt lgkmcnt(6)
	v_mfma_f32_16x16x32_bf16 v[16:19], v[168:171], v[86:89], v[16:19]
	ds_write_b128 v74, v[220:223] offset:49152
	v_mfma_f32_16x16x32_bf16 v[20:23], v[168:171], v[90:93], v[20:23]
	ds_write_b128 v74, v[224:227] offset:53248
	v_mfma_f32_16x16x32_bf16 v[24:27], v[168:171], v[112:115], v[24:27]
	ds_write_b128 v74, v[228:231] offset:57344
	v_mfma_f32_16x16x32_bf16 v[28:31], v[168:171], v[252:255], v[28:31]
	ds_write_b128 v74, v[232:235] offset:61440
	s_waitcnt lgkmcnt(9)
	v_mfma_f32_16x16x32_bf16 v[32:35], v[244:247], v[86:89], v[32:35]
	global_load_dwordx4 v[204:207], v66, s[98:99] offset:1408
	v_mfma_f32_16x16x32_bf16 v[36:39], v[244:247], v[90:93], v[36:39]
	global_load_dwordx4 v[208:211], v67, s[98:99] offset:1408
	v_mfma_f32_16x16x32_bf16 v[40:43], v[244:247], v[112:115], v[40:43]
	global_load_dwordx4 v[212:215], v68, s[98:99] offset:1408
	v_mfma_f32_16x16x32_bf16 v[44:47], v[244:247], v[252:255], v[44:47]
	global_load_dwordx4 v[216:219], v69, s[98:99] offset:1408
	s_waitcnt lgkmcnt(8)
	v_mfma_f32_16x16x32_bf16 v[48:51], v[248:251], v[86:89], v[48:51]
	global_load_dwordx4 v[220:223], v66, s[100:101] offset:1408
	v_mfma_f32_16x16x32_bf16 v[52:55], v[248:251], v[90:93], v[52:55]
	global_load_dwordx4 v[224:227], v67, s[100:101] offset:1408
	v_mfma_f32_16x16x32_bf16 v[56:59], v[248:251], v[112:115], v[56:59]
	global_load_dwordx4 v[228:231], v68, s[100:101] offset:1408
	v_mfma_f32_16x16x32_bf16 v[60:63], v[248:251], v[252:255], v[60:63]
	global_load_dwordx4 v[232:235], v69, s[100:101] offset:1408
	s_waitcnt lgkmcnt(0)
	s_barrier
	ds_read_b128 v[120:123], v239 offset:32768
	ds_read_b128 v[140:143], v241 offset:32768
	ds_read_b128 v[152:155], v241 offset:34816
	ds_read_b128 v[156:159], v241 offset:36864
	ds_read_b128 v[160:163], v241 offset:38912
	ds_read_b128 v[124:127], v239 offset:34816
	ds_read_b128 v[128:131], v239 offset:36864
	ds_read_b128 v[132:135], v239 offset:38912
	s_waitcnt lgkmcnt(6)
	v_mfma_f32_16x16x32_bf16 v[0:3], v[120:123], v[140:143], v[0:3]
	ds_read_b128 v[164:167], v240 offset:32768
	s_waitcnt lgkmcnt(6)
	v_mfma_f32_16x16x32_bf16 v[4:7], v[120:123], v[152:155], v[4:7]
	ds_read_b128 v[86:89], v242 offset:32768
	s_waitcnt lgkmcnt(6)
	v_mfma_f32_16x16x32_bf16 v[8:11], v[120:123], v[156:159], v[8:11]
	ds_read_b128 v[90:93], v242 offset:34816
	s_waitcnt lgkmcnt(6)
	v_mfma_f32_16x16x32_bf16 v[12:15], v[120:123], v[160:163], v[12:15]
	ds_read_b128 v[112:115], v242 offset:36864
	s_waitcnt lgkmcnt(6)
	v_mfma_f32_16x16x32_bf16 v[16:19], v[124:127], v[140:143], v[16:19]
	ds_read_b128 v[252:255], v242 offset:38912
	v_mfma_f32_16x16x32_bf16 v[20:23], v[124:127], v[152:155], v[20:23]
	ds_read_b128 v[168:171], v240 offset:34816
	v_mfma_f32_16x16x32_bf16 v[24:27], v[124:127], v[156:159], v[24:27]
	ds_read_b128 v[244:247], v240 offset:36864
	v_mfma_f32_16x16x32_bf16 v[28:31], v[124:127], v[160:163], v[28:31]
	ds_read_b128 v[248:251], v240 offset:38912
	s_waitcnt lgkmcnt(9)
	v_mfma_f32_16x16x32_bf16 v[32:35], v[128:131], v[140:143], v[32:35]
	v_mfma_f32_16x16x32_bf16 v[36:39], v[128:131], v[152:155], v[36:39]
	v_mfma_f32_16x16x32_bf16 v[40:43], v[128:131], v[156:159], v[40:43]
	v_mfma_f32_16x16x32_bf16 v[44:47], v[128:131], v[160:163], v[44:47]
	s_waitcnt lgkmcnt(8)
	v_mfma_f32_16x16x32_bf16 v[48:51], v[132:135], v[140:143], v[48:51]
	v_mfma_f32_16x16x32_bf16 v[52:55], v[132:135], v[152:155], v[52:55]
	v_mfma_f32_16x16x32_bf16 v[56:59], v[132:135], v[156:159], v[56:59]
	v_mfma_f32_16x16x32_bf16 v[60:63], v[132:135], v[160:163], v[60:63]
	s_waitcnt lgkmcnt(6)
	v_mfma_f32_16x16x32_bf16 v[0:3], v[164:167], v[86:89], v[0:3]
	s_waitcnt vmcnt(8)
	ds_write_b128 v74, v[172:175]
	s_waitcnt lgkmcnt(6)
	v_mfma_f32_16x16x32_bf16 v[4:7], v[164:167], v[90:93], v[4:7]
	ds_write_b128 v74, v[176:179] offset:4096
	s_waitcnt lgkmcnt(6)
	v_mfma_f32_16x16x32_bf16 v[8:11], v[164:167], v[112:115], v[8:11]
	ds_write_b128 v74, v[180:183] offset:8192
	s_waitcnt lgkmcnt(6)
	v_mfma_f32_16x16x32_bf16 v[12:15], v[164:167], v[252:255], v[12:15]
	ds_write_b128 v74, v[184:187] offset:12288
	s_waitcnt lgkmcnt(6)
	v_mfma_f32_16x16x32_bf16 v[16:19], v[168:171], v[86:89], v[16:19]
	ds_write_b128 v74, v[188:191] offset:16384
	v_mfma_f32_16x16x32_bf16 v[20:23], v[168:171], v[90:93], v[20:23]
	ds_write_b128 v74, v[192:195] offset:20480
	v_mfma_f32_16x16x32_bf16 v[24:27], v[168:171], v[112:115], v[24:27]
	ds_write_b128 v74, v[196:199] offset:24576
	v_mfma_f32_16x16x32_bf16 v[28:31], v[168:171], v[252:255], v[28:31]
	ds_write_b128 v74, v[200:203] offset:28672
	s_waitcnt lgkmcnt(9)
	v_mfma_f32_16x16x32_bf16 v[32:35], v[244:247], v[86:89], v[32:35]
	global_load_dwordx4 v[172:175], v66, s[98:99] offset:1536
	v_mfma_f32_16x16x32_bf16 v[36:39], v[244:247], v[90:93], v[36:39]
	global_load_dwordx4 v[176:179], v67, s[98:99] offset:1536
	v_mfma_f32_16x16x32_bf16 v[40:43], v[244:247], v[112:115], v[40:43]
	global_load_dwordx4 v[180:183], v68, s[98:99] offset:1536
	v_mfma_f32_16x16x32_bf16 v[44:47], v[244:247], v[252:255], v[44:47]
	global_load_dwordx4 v[184:187], v69, s[98:99] offset:1536
	s_waitcnt lgkmcnt(8)
	v_mfma_f32_16x16x32_bf16 v[48:51], v[248:251], v[86:89], v[48:51]
	global_load_dwordx4 v[188:191], v66, s[100:101] offset:1536
	v_mfma_f32_16x16x32_bf16 v[52:55], v[248:251], v[90:93], v[52:55]
	global_load_dwordx4 v[192:195], v67, s[100:101] offset:1536
	v_mfma_f32_16x16x32_bf16 v[56:59], v[248:251], v[112:115], v[56:59]
	global_load_dwordx4 v[196:199], v68, s[100:101] offset:1536
	v_mfma_f32_16x16x32_bf16 v[60:63], v[248:251], v[252:255], v[60:63]
	global_load_dwordx4 v[200:203], v69, s[100:101] offset:1536
	s_waitcnt lgkmcnt(0)
	s_barrier
	ds_read_b128 v[120:123], v239
	ds_read_b128 v[140:143], v241
	ds_read_b128 v[152:155], v241 offset:2048
	ds_read_b128 v[156:159], v241 offset:4096
	ds_read_b128 v[160:163], v241 offset:6144
	ds_read_b128 v[124:127], v239 offset:2048
	ds_read_b128 v[128:131], v239 offset:4096
	ds_read_b128 v[132:135], v239 offset:6144
	s_waitcnt lgkmcnt(6)
	v_mfma_f32_16x16x32_bf16 v[0:3], v[120:123], v[140:143], v[0:3]
	ds_read_b128 v[164:167], v240
	s_waitcnt lgkmcnt(6)
	v_mfma_f32_16x16x32_bf16 v[4:7], v[120:123], v[152:155], v[4:7]
	ds_read_b128 v[86:89], v242
	s_waitcnt lgkmcnt(6)
	v_mfma_f32_16x16x32_bf16 v[8:11], v[120:123], v[156:159], v[8:11]
	ds_read_b128 v[90:93], v242 offset:2048
	s_waitcnt lgkmcnt(6)
	v_mfma_f32_16x16x32_bf16 v[12:15], v[120:123], v[160:163], v[12:15]
	ds_read_b128 v[112:115], v242 offset:4096
	s_waitcnt lgkmcnt(6)
	v_mfma_f32_16x16x32_bf16 v[16:19], v[124:127], v[140:143], v[16:19]
	ds_read_b128 v[252:255], v242 offset:6144
	v_mfma_f32_16x16x32_bf16 v[20:23], v[124:127], v[152:155], v[20:23]
	ds_read_b128 v[168:171], v240 offset:2048
	v_mfma_f32_16x16x32_bf16 v[24:27], v[124:127], v[156:159], v[24:27]
	ds_read_b128 v[244:247], v240 offset:4096
	v_mfma_f32_16x16x32_bf16 v[28:31], v[124:127], v[160:163], v[28:31]
	ds_read_b128 v[248:251], v240 offset:6144
	s_waitcnt lgkmcnt(9)
	v_mfma_f32_16x16x32_bf16 v[32:35], v[128:131], v[140:143], v[32:35]
	v_mfma_f32_16x16x32_bf16 v[36:39], v[128:131], v[152:155], v[36:39]
	v_mfma_f32_16x16x32_bf16 v[40:43], v[128:131], v[156:159], v[40:43]
	v_mfma_f32_16x16x32_bf16 v[44:47], v[128:131], v[160:163], v[44:47]
	s_waitcnt lgkmcnt(8)
	v_mfma_f32_16x16x32_bf16 v[48:51], v[132:135], v[140:143], v[48:51]
	v_mfma_f32_16x16x32_bf16 v[52:55], v[132:135], v[152:155], v[52:55]
	v_mfma_f32_16x16x32_bf16 v[56:59], v[132:135], v[156:159], v[56:59]
	v_mfma_f32_16x16x32_bf16 v[60:63], v[132:135], v[160:163], v[60:63]
	s_waitcnt lgkmcnt(6)
	v_mfma_f32_16x16x32_bf16 v[0:3], v[164:167], v[86:89], v[0:3]
	s_waitcnt vmcnt(8)
	ds_write_b128 v74, v[204:207] offset:32768
	s_waitcnt lgkmcnt(6)
	v_mfma_f32_16x16x32_bf16 v[4:7], v[164:167], v[90:93], v[4:7]
	ds_write_b128 v74, v[208:211] offset:36864
	s_waitcnt lgkmcnt(6)
	v_mfma_f32_16x16x32_bf16 v[8:11], v[164:167], v[112:115], v[8:11]
	ds_write_b128 v74, v[212:215] offset:40960
	s_waitcnt lgkmcnt(6)
	v_mfma_f32_16x16x32_bf16 v[12:15], v[164:167], v[252:255], v[12:15]
	ds_write_b128 v74, v[216:219] offset:45056
	s_waitcnt lgkmcnt(6)
	v_mfma_f32_16x16x32_bf16 v[16:19], v[168:171], v[86:89], v[16:19]
	ds_write_b128 v74, v[220:223] offset:49152
	v_mfma_f32_16x16x32_bf16 v[20:23], v[168:171], v[90:93], v[20:23]
	ds_write_b128 v74, v[224:227] offset:53248
	v_mfma_f32_16x16x32_bf16 v[24:27], v[168:171], v[112:115], v[24:27]
	ds_write_b128 v74, v[228:231] offset:57344
	v_mfma_f32_16x16x32_bf16 v[28:31], v[168:171], v[252:255], v[28:31]
	ds_write_b128 v74, v[232:235] offset:61440
	s_waitcnt lgkmcnt(9)
	v_mfma_f32_16x16x32_bf16 v[32:35], v[244:247], v[86:89], v[32:35]
	global_load_dwordx4 v[204:207], v66, s[98:99] offset:1664
	v_mfma_f32_16x16x32_bf16 v[36:39], v[244:247], v[90:93], v[36:39]
	global_load_dwordx4 v[208:211], v67, s[98:99] offset:1664
	v_mfma_f32_16x16x32_bf16 v[40:43], v[244:247], v[112:115], v[40:43]
	global_load_dwordx4 v[212:215], v68, s[98:99] offset:1664
	v_mfma_f32_16x16x32_bf16 v[44:47], v[244:247], v[252:255], v[44:47]
	global_load_dwordx4 v[216:219], v69, s[98:99] offset:1664
	s_waitcnt lgkmcnt(8)
	v_mfma_f32_16x16x32_bf16 v[48:51], v[248:251], v[86:89], v[48:51]
	global_load_dwordx4 v[220:223], v66, s[100:101] offset:1664
	v_mfma_f32_16x16x32_bf16 v[52:55], v[248:251], v[90:93], v[52:55]
	global_load_dwordx4 v[224:227], v67, s[100:101] offset:1664
	v_mfma_f32_16x16x32_bf16 v[56:59], v[248:251], v[112:115], v[56:59]
	global_load_dwordx4 v[228:231], v68, s[100:101] offset:1664
	v_mfma_f32_16x16x32_bf16 v[60:63], v[248:251], v[252:255], v[60:63]
	global_load_dwordx4 v[232:235], v69, s[100:101] offset:1664
	s_waitcnt lgkmcnt(0)
	s_barrier
	ds_read_b128 v[120:123], v239 offset:32768
	ds_read_b128 v[140:143], v241 offset:32768
	ds_read_b128 v[152:155], v241 offset:34816
	ds_read_b128 v[156:159], v241 offset:36864
	ds_read_b128 v[160:163], v241 offset:38912
	ds_read_b128 v[124:127], v239 offset:34816
	ds_read_b128 v[128:131], v239 offset:36864
	ds_read_b128 v[132:135], v239 offset:38912
	s_waitcnt lgkmcnt(6)
	v_mfma_f32_16x16x32_bf16 v[0:3], v[120:123], v[140:143], v[0:3]
	ds_read_b128 v[164:167], v240 offset:32768
	s_waitcnt lgkmcnt(6)
	v_mfma_f32_16x16x32_bf16 v[4:7], v[120:123], v[152:155], v[4:7]
	ds_read_b128 v[86:89], v242 offset:32768
	s_waitcnt lgkmcnt(6)
	v_mfma_f32_16x16x32_bf16 v[8:11], v[120:123], v[156:159], v[8:11]
	ds_read_b128 v[90:93], v242 offset:34816
	s_waitcnt lgkmcnt(6)
	v_mfma_f32_16x16x32_bf16 v[12:15], v[120:123], v[160:163], v[12:15]
	ds_read_b128 v[112:115], v242 offset:36864
	s_waitcnt lgkmcnt(6)
	v_mfma_f32_16x16x32_bf16 v[16:19], v[124:127], v[140:143], v[16:19]
	ds_read_b128 v[252:255], v242 offset:38912
	v_mfma_f32_16x16x32_bf16 v[20:23], v[124:127], v[152:155], v[20:23]
	ds_read_b128 v[168:171], v240 offset:34816
	v_mfma_f32_16x16x32_bf16 v[24:27], v[124:127], v[156:159], v[24:27]
	ds_read_b128 v[244:247], v240 offset:36864
	v_mfma_f32_16x16x32_bf16 v[28:31], v[124:127], v[160:163], v[28:31]
	ds_read_b128 v[248:251], v240 offset:38912
	s_waitcnt lgkmcnt(9)
	v_mfma_f32_16x16x32_bf16 v[32:35], v[128:131], v[140:143], v[32:35]
	v_mfma_f32_16x16x32_bf16 v[36:39], v[128:131], v[152:155], v[36:39]
	v_mfma_f32_16x16x32_bf16 v[40:43], v[128:131], v[156:159], v[40:43]
	v_mfma_f32_16x16x32_bf16 v[44:47], v[128:131], v[160:163], v[44:47]
	s_waitcnt lgkmcnt(8)
	v_mfma_f32_16x16x32_bf16 v[48:51], v[132:135], v[140:143], v[48:51]
	v_mfma_f32_16x16x32_bf16 v[52:55], v[132:135], v[152:155], v[52:55]
	v_mfma_f32_16x16x32_bf16 v[56:59], v[132:135], v[156:159], v[56:59]
	v_mfma_f32_16x16x32_bf16 v[60:63], v[132:135], v[160:163], v[60:63]
	s_waitcnt lgkmcnt(6)
	v_mfma_f32_16x16x32_bf16 v[0:3], v[164:167], v[86:89], v[0:3]
	s_waitcnt vmcnt(8)
	ds_write_b128 v74, v[172:175]
	s_waitcnt lgkmcnt(6)
	v_mfma_f32_16x16x32_bf16 v[4:7], v[164:167], v[90:93], v[4:7]
	ds_write_b128 v74, v[176:179] offset:4096
	s_waitcnt lgkmcnt(6)
	v_mfma_f32_16x16x32_bf16 v[8:11], v[164:167], v[112:115], v[8:11]
	ds_write_b128 v74, v[180:183] offset:8192
	s_waitcnt lgkmcnt(6)
	v_mfma_f32_16x16x32_bf16 v[12:15], v[164:167], v[252:255], v[12:15]
	ds_write_b128 v74, v[184:187] offset:12288
	s_waitcnt lgkmcnt(6)
	v_mfma_f32_16x16x32_bf16 v[16:19], v[168:171], v[86:89], v[16:19]
	ds_write_b128 v74, v[188:191] offset:16384
	v_mfma_f32_16x16x32_bf16 v[20:23], v[168:171], v[90:93], v[20:23]
	ds_write_b128 v74, v[192:195] offset:20480
	v_mfma_f32_16x16x32_bf16 v[24:27], v[168:171], v[112:115], v[24:27]
	ds_write_b128 v74, v[196:199] offset:24576
	v_mfma_f32_16x16x32_bf16 v[28:31], v[168:171], v[252:255], v[28:31]
	ds_write_b128 v74, v[200:203] offset:28672
	s_waitcnt lgkmcnt(9)
	v_mfma_f32_16x16x32_bf16 v[32:35], v[244:247], v[86:89], v[32:35]
	global_load_dwordx4 v[172:175], v66, s[98:99] offset:1792
	v_mfma_f32_16x16x32_bf16 v[36:39], v[244:247], v[90:93], v[36:39]
	global_load_dwordx4 v[176:179], v67, s[98:99] offset:1792
	v_mfma_f32_16x16x32_bf16 v[40:43], v[244:247], v[112:115], v[40:43]
	global_load_dwordx4 v[180:183], v68, s[98:99] offset:1792
	v_mfma_f32_16x16x32_bf16 v[44:47], v[244:247], v[252:255], v[44:47]
	global_load_dwordx4 v[184:187], v69, s[98:99] offset:1792
	s_waitcnt lgkmcnt(8)
	v_mfma_f32_16x16x32_bf16 v[48:51], v[248:251], v[86:89], v[48:51]
	global_load_dwordx4 v[188:191], v66, s[100:101] offset:1792
	v_mfma_f32_16x16x32_bf16 v[52:55], v[248:251], v[90:93], v[52:55]
	global_load_dwordx4 v[192:195], v67, s[100:101] offset:1792
	v_mfma_f32_16x16x32_bf16 v[56:59], v[248:251], v[112:115], v[56:59]
	global_load_dwordx4 v[196:199], v68, s[100:101] offset:1792
	v_mfma_f32_16x16x32_bf16 v[60:63], v[248:251], v[252:255], v[60:63]
	global_load_dwordx4 v[200:203], v69, s[100:101] offset:1792
	s_waitcnt lgkmcnt(0)
	s_barrier
	ds_read_b128 v[120:123], v239
	ds_read_b128 v[140:143], v241
	ds_read_b128 v[152:155], v241 offset:2048
	ds_read_b128 v[156:159], v241 offset:4096
	ds_read_b128 v[160:163], v241 offset:6144
	ds_read_b128 v[124:127], v239 offset:2048
	ds_read_b128 v[128:131], v239 offset:4096
	ds_read_b128 v[132:135], v239 offset:6144
	s_waitcnt lgkmcnt(6)
	v_mfma_f32_16x16x32_bf16 v[0:3], v[120:123], v[140:143], v[0:3]
	ds_read_b128 v[164:167], v240
	s_waitcnt lgkmcnt(6)
	v_mfma_f32_16x16x32_bf16 v[4:7], v[120:123], v[152:155], v[4:7]
	ds_read_b128 v[86:89], v242
	s_waitcnt lgkmcnt(6)
	v_mfma_f32_16x16x32_bf16 v[8:11], v[120:123], v[156:159], v[8:11]
	ds_read_b128 v[90:93], v242 offset:2048
	s_waitcnt lgkmcnt(6)
	v_mfma_f32_16x16x32_bf16 v[12:15], v[120:123], v[160:163], v[12:15]
	ds_read_b128 v[112:115], v242 offset:4096
	s_waitcnt lgkmcnt(6)
	v_mfma_f32_16x16x32_bf16 v[16:19], v[124:127], v[140:143], v[16:19]
	ds_read_b128 v[252:255], v242 offset:6144
	v_mfma_f32_16x16x32_bf16 v[20:23], v[124:127], v[152:155], v[20:23]
	ds_read_b128 v[168:171], v240 offset:2048
	v_mfma_f32_16x16x32_bf16 v[24:27], v[124:127], v[156:159], v[24:27]
	ds_read_b128 v[244:247], v240 offset:4096
	v_mfma_f32_16x16x32_bf16 v[28:31], v[124:127], v[160:163], v[28:31]
	ds_read_b128 v[248:251], v240 offset:6144
	s_waitcnt lgkmcnt(9)
	v_mfma_f32_16x16x32_bf16 v[32:35], v[128:131], v[140:143], v[32:35]
	v_mfma_f32_16x16x32_bf16 v[36:39], v[128:131], v[152:155], v[36:39]
	v_mfma_f32_16x16x32_bf16 v[40:43], v[128:131], v[156:159], v[40:43]
	v_mfma_f32_16x16x32_bf16 v[44:47], v[128:131], v[160:163], v[44:47]
	s_waitcnt lgkmcnt(8)
	v_mfma_f32_16x16x32_bf16 v[48:51], v[132:135], v[140:143], v[48:51]
	v_mfma_f32_16x16x32_bf16 v[52:55], v[132:135], v[152:155], v[52:55]
	v_mfma_f32_16x16x32_bf16 v[56:59], v[132:135], v[156:159], v[56:59]
	v_mfma_f32_16x16x32_bf16 v[60:63], v[132:135], v[160:163], v[60:63]
	s_waitcnt lgkmcnt(6)
	v_mfma_f32_16x16x32_bf16 v[0:3], v[164:167], v[86:89], v[0:3]
	s_waitcnt vmcnt(8)
	ds_write_b128 v74, v[204:207] offset:32768
	s_waitcnt lgkmcnt(6)
	v_mfma_f32_16x16x32_bf16 v[4:7], v[164:167], v[90:93], v[4:7]
	ds_write_b128 v74, v[208:211] offset:36864
	s_waitcnt lgkmcnt(6)
	v_mfma_f32_16x16x32_bf16 v[8:11], v[164:167], v[112:115], v[8:11]
	ds_write_b128 v74, v[212:215] offset:40960
	s_waitcnt lgkmcnt(6)
	v_mfma_f32_16x16x32_bf16 v[12:15], v[164:167], v[252:255], v[12:15]
	ds_write_b128 v74, v[216:219] offset:45056
	s_waitcnt lgkmcnt(6)
	v_mfma_f32_16x16x32_bf16 v[16:19], v[168:171], v[86:89], v[16:19]
	ds_write_b128 v74, v[220:223] offset:49152
	v_mfma_f32_16x16x32_bf16 v[20:23], v[168:171], v[90:93], v[20:23]
	ds_write_b128 v74, v[224:227] offset:53248
	v_mfma_f32_16x16x32_bf16 v[24:27], v[168:171], v[112:115], v[24:27]
	ds_write_b128 v74, v[228:231] offset:57344
	v_mfma_f32_16x16x32_bf16 v[28:31], v[168:171], v[252:255], v[28:31]
	ds_write_b128 v74, v[232:235] offset:61440
	s_waitcnt lgkmcnt(9)
	v_mfma_f32_16x16x32_bf16 v[32:35], v[244:247], v[86:89], v[32:35]
	global_load_dwordx4 v[204:207], v66, s[98:99] offset:1920
	v_mfma_f32_16x16x32_bf16 v[36:39], v[244:247], v[90:93], v[36:39]
	global_load_dwordx4 v[208:211], v67, s[98:99] offset:1920
	v_mfma_f32_16x16x32_bf16 v[40:43], v[244:247], v[112:115], v[40:43]
	global_load_dwordx4 v[212:215], v68, s[98:99] offset:1920
	v_mfma_f32_16x16x32_bf16 v[44:47], v[244:247], v[252:255], v[44:47]
	global_load_dwordx4 v[216:219], v69, s[98:99] offset:1920
	s_waitcnt lgkmcnt(8)
	v_mfma_f32_16x16x32_bf16 v[48:51], v[248:251], v[86:89], v[48:51]
	global_load_dwordx4 v[220:223], v66, s[100:101] offset:1920
	v_mfma_f32_16x16x32_bf16 v[52:55], v[248:251], v[90:93], v[52:55]
	global_load_dwordx4 v[224:227], v67, s[100:101] offset:1920
	v_mfma_f32_16x16x32_bf16 v[56:59], v[248:251], v[112:115], v[56:59]
	global_load_dwordx4 v[228:231], v68, s[100:101] offset:1920
	v_mfma_f32_16x16x32_bf16 v[60:63], v[248:251], v[252:255], v[60:63]
	global_load_dwordx4 v[232:235], v69, s[100:101] offset:1920
	s_waitcnt lgkmcnt(0)
	s_barrier
	ds_read_b128 v[120:123], v239 offset:32768
	ds_read_b128 v[140:143], v241 offset:32768
	ds_read_b128 v[152:155], v241 offset:34816
	ds_read_b128 v[156:159], v241 offset:36864
	ds_read_b128 v[160:163], v241 offset:38912
	ds_read_b128 v[124:127], v239 offset:34816
	ds_read_b128 v[128:131], v239 offset:36864
	ds_read_b128 v[132:135], v239 offset:38912
	s_waitcnt lgkmcnt(6)
	v_mfma_f32_16x16x32_bf16 v[0:3], v[120:123], v[140:143], v[0:3]
	ds_read_b128 v[164:167], v240 offset:32768
	s_waitcnt lgkmcnt(6)
	v_mfma_f32_16x16x32_bf16 v[4:7], v[120:123], v[152:155], v[4:7]
	ds_read_b128 v[86:89], v242 offset:32768
	s_waitcnt lgkmcnt(6)
	v_mfma_f32_16x16x32_bf16 v[8:11], v[120:123], v[156:159], v[8:11]
	ds_read_b128 v[90:93], v242 offset:34816
	s_waitcnt lgkmcnt(6)
	v_mfma_f32_16x16x32_bf16 v[12:15], v[120:123], v[160:163], v[12:15]
	ds_read_b128 v[112:115], v242 offset:36864
	s_waitcnt lgkmcnt(6)
	v_mfma_f32_16x16x32_bf16 v[16:19], v[124:127], v[140:143], v[16:19]
	ds_read_b128 v[252:255], v242 offset:38912
	v_mfma_f32_16x16x32_bf16 v[20:23], v[124:127], v[152:155], v[20:23]
	ds_read_b128 v[168:171], v240 offset:34816
	v_mfma_f32_16x16x32_bf16 v[24:27], v[124:127], v[156:159], v[24:27]
	ds_read_b128 v[244:247], v240 offset:36864
	v_mfma_f32_16x16x32_bf16 v[28:31], v[124:127], v[160:163], v[28:31]
	ds_read_b128 v[248:251], v240 offset:38912
	s_waitcnt lgkmcnt(9)
	v_mfma_f32_16x16x32_bf16 v[32:35], v[128:131], v[140:143], v[32:35]
	v_mfma_f32_16x16x32_bf16 v[36:39], v[128:131], v[152:155], v[36:39]
	v_mfma_f32_16x16x32_bf16 v[40:43], v[128:131], v[156:159], v[40:43]
	v_mfma_f32_16x16x32_bf16 v[44:47], v[128:131], v[160:163], v[44:47]
	s_waitcnt lgkmcnt(8)
	v_mfma_f32_16x16x32_bf16 v[48:51], v[132:135], v[140:143], v[48:51]
	v_mfma_f32_16x16x32_bf16 v[52:55], v[132:135], v[152:155], v[52:55]
	v_mfma_f32_16x16x32_bf16 v[56:59], v[132:135], v[156:159], v[56:59]
	v_mfma_f32_16x16x32_bf16 v[60:63], v[132:135], v[160:163], v[60:63]
	s_waitcnt lgkmcnt(6)
	v_mfma_f32_16x16x32_bf16 v[0:3], v[164:167], v[86:89], v[0:3]
	s_waitcnt vmcnt(8)
	ds_write_b128 v74, v[172:175]
	s_waitcnt lgkmcnt(6)
	v_mfma_f32_16x16x32_bf16 v[4:7], v[164:167], v[90:93], v[4:7]
	ds_write_b128 v74, v[176:179] offset:4096
	s_waitcnt lgkmcnt(6)
	v_mfma_f32_16x16x32_bf16 v[8:11], v[164:167], v[112:115], v[8:11]
	ds_write_b128 v74, v[180:183] offset:8192
	s_waitcnt lgkmcnt(6)
	v_mfma_f32_16x16x32_bf16 v[12:15], v[164:167], v[252:255], v[12:15]
	ds_write_b128 v74, v[184:187] offset:12288
	s_waitcnt lgkmcnt(6)
	v_mfma_f32_16x16x32_bf16 v[16:19], v[168:171], v[86:89], v[16:19]
	ds_write_b128 v74, v[188:191] offset:16384
	v_mfma_f32_16x16x32_bf16 v[20:23], v[168:171], v[90:93], v[20:23]
	ds_write_b128 v74, v[192:195] offset:20480
	v_mfma_f32_16x16x32_bf16 v[24:27], v[168:171], v[112:115], v[24:27]
	ds_write_b128 v74, v[196:199] offset:24576
	v_mfma_f32_16x16x32_bf16 v[28:31], v[168:171], v[252:255], v[28:31]
	ds_write_b128 v74, v[200:203] offset:28672
	s_waitcnt lgkmcnt(9)
	v_mfma_f32_16x16x32_bf16 v[32:35], v[244:247], v[86:89], v[32:35]
	v_mfma_f32_16x16x32_bf16 v[36:39], v[244:247], v[90:93], v[36:39]
	v_mfma_f32_16x16x32_bf16 v[40:43], v[244:247], v[112:115], v[40:43]
	v_mfma_f32_16x16x32_bf16 v[44:47], v[244:247], v[252:255], v[44:47]
	s_waitcnt lgkmcnt(8)
	v_mfma_f32_16x16x32_bf16 v[48:51], v[248:251], v[86:89], v[48:51]
	v_mfma_f32_16x16x32_bf16 v[52:55], v[248:251], v[90:93], v[52:55]
	v_mfma_f32_16x16x32_bf16 v[56:59], v[248:251], v[112:115], v[56:59]
	v_mfma_f32_16x16x32_bf16 v[60:63], v[248:251], v[252:255], v[60:63]
	s_waitcnt lgkmcnt(0)
	s_barrier
	ds_read_b128 v[120:123], v239
	ds_read_b128 v[140:143], v241
	ds_read_b128 v[152:155], v241 offset:2048
	ds_read_b128 v[156:159], v241 offset:4096
	ds_read_b128 v[160:163], v241 offset:6144
	ds_read_b128 v[124:127], v239 offset:2048
	ds_read_b128 v[128:131], v239 offset:4096
	ds_read_b128 v[132:135], v239 offset:6144
	s_waitcnt lgkmcnt(6)
	v_mfma_f32_16x16x32_bf16 v[0:3], v[120:123], v[140:143], v[0:3]
	ds_read_b128 v[164:167], v240
	s_waitcnt lgkmcnt(6)
	v_mfma_f32_16x16x32_bf16 v[4:7], v[120:123], v[152:155], v[4:7]
	ds_read_b128 v[86:89], v242
	s_waitcnt lgkmcnt(6)
	v_mfma_f32_16x16x32_bf16 v[8:11], v[120:123], v[156:159], v[8:11]
	ds_read_b128 v[90:93], v242 offset:2048
	s_waitcnt lgkmcnt(6)
	v_mfma_f32_16x16x32_bf16 v[12:15], v[120:123], v[160:163], v[12:15]
	ds_read_b128 v[112:115], v242 offset:4096
	s_waitcnt lgkmcnt(6)
	v_mfma_f32_16x16x32_bf16 v[16:19], v[124:127], v[140:143], v[16:19]
	ds_read_b128 v[252:255], v242 offset:6144
	v_mfma_f32_16x16x32_bf16 v[20:23], v[124:127], v[152:155], v[20:23]
	ds_read_b128 v[168:171], v240 offset:2048
	v_mfma_f32_16x16x32_bf16 v[24:27], v[124:127], v[156:159], v[24:27]
	ds_read_b128 v[244:247], v240 offset:4096
	v_mfma_f32_16x16x32_bf16 v[28:31], v[124:127], v[160:163], v[28:31]
	ds_read_b128 v[248:251], v240 offset:6144
	s_waitcnt lgkmcnt(9)
	v_mfma_f32_16x16x32_bf16 v[32:35], v[128:131], v[140:143], v[32:35]
	v_mfma_f32_16x16x32_bf16 v[36:39], v[128:131], v[152:155], v[36:39]
	v_mfma_f32_16x16x32_bf16 v[40:43], v[128:131], v[156:159], v[40:43]
	v_mfma_f32_16x16x32_bf16 v[44:47], v[128:131], v[160:163], v[44:47]
	s_waitcnt lgkmcnt(8)
	v_mfma_f32_16x16x32_bf16 v[48:51], v[132:135], v[140:143], v[48:51]
	v_mfma_f32_16x16x32_bf16 v[52:55], v[132:135], v[152:155], v[52:55]
	v_mfma_f32_16x16x32_bf16 v[56:59], v[132:135], v[156:159], v[56:59]
	v_mfma_f32_16x16x32_bf16 v[60:63], v[132:135], v[160:163], v[60:63]
	s_waitcnt lgkmcnt(6)
	v_mfma_f32_16x16x32_bf16 v[0:3], v[164:167], v[86:89], v[0:3]
	s_waitcnt vmcnt(0)
	ds_write_b128 v74, v[204:207] offset:32768
	s_waitcnt lgkmcnt(6)
	v_mfma_f32_16x16x32_bf16 v[4:7], v[164:167], v[90:93], v[4:7]
	ds_write_b128 v74, v[208:211] offset:36864
	s_waitcnt lgkmcnt(6)
	v_mfma_f32_16x16x32_bf16 v[8:11], v[164:167], v[112:115], v[8:11]
	ds_write_b128 v74, v[212:215] offset:40960
	s_waitcnt lgkmcnt(6)
	v_mfma_f32_16x16x32_bf16 v[12:15], v[164:167], v[252:255], v[12:15]
	ds_write_b128 v74, v[216:219] offset:45056
	s_waitcnt lgkmcnt(6)
	v_mfma_f32_16x16x32_bf16 v[16:19], v[168:171], v[86:89], v[16:19]
	ds_write_b128 v74, v[220:223] offset:49152
	v_mfma_f32_16x16x32_bf16 v[20:23], v[168:171], v[90:93], v[20:23]
	ds_write_b128 v74, v[224:227] offset:53248
	v_mfma_f32_16x16x32_bf16 v[24:27], v[168:171], v[112:115], v[24:27]
	ds_write_b128 v74, v[228:231] offset:57344
	v_mfma_f32_16x16x32_bf16 v[28:31], v[168:171], v[252:255], v[28:31]
	ds_write_b128 v74, v[232:235] offset:61440
	s_waitcnt lgkmcnt(9)
	v_mfma_f32_16x16x32_bf16 v[32:35], v[244:247], v[86:89], v[32:35]
	v_mfma_f32_16x16x32_bf16 v[36:39], v[244:247], v[90:93], v[36:39]
	v_mfma_f32_16x16x32_bf16 v[40:43], v[244:247], v[112:115], v[40:43]
	v_mfma_f32_16x16x32_bf16 v[44:47], v[244:247], v[252:255], v[44:47]
	s_waitcnt lgkmcnt(8)
	v_mfma_f32_16x16x32_bf16 v[48:51], v[248:251], v[86:89], v[48:51]
	v_mfma_f32_16x16x32_bf16 v[52:55], v[248:251], v[90:93], v[52:55]
	v_mfma_f32_16x16x32_bf16 v[56:59], v[248:251], v[112:115], v[56:59]
	v_mfma_f32_16x16x32_bf16 v[60:63], v[248:251], v[252:255], v[60:63]
	s_waitcnt lgkmcnt(0)
	s_barrier
	ds_read_b128 v[120:123], v239 offset:32768
	ds_read_b128 v[140:143], v241 offset:32768
	ds_read_b128 v[152:155], v241 offset:34816
	ds_read_b128 v[156:159], v241 offset:36864
	ds_read_b128 v[160:163], v241 offset:38912
	ds_read_b128 v[124:127], v239 offset:34816
	ds_read_b128 v[128:131], v239 offset:36864
	ds_read_b128 v[132:135], v239 offset:38912
	s_waitcnt lgkmcnt(6)
	v_mfma_f32_16x16x32_bf16 v[0:3], v[120:123], v[140:143], v[0:3]
	ds_read_b128 v[164:167], v240 offset:32768
	s_waitcnt lgkmcnt(6)
	v_mfma_f32_16x16x32_bf16 v[4:7], v[120:123], v[152:155], v[4:7]
	ds_read_b128 v[86:89], v242 offset:32768
	s_waitcnt lgkmcnt(6)
	v_mfma_f32_16x16x32_bf16 v[8:11], v[120:123], v[156:159], v[8:11]
	ds_read_b128 v[90:93], v242 offset:34816
	s_waitcnt lgkmcnt(6)
	v_mfma_f32_16x16x32_bf16 v[12:15], v[120:123], v[160:163], v[12:15]
	ds_read_b128 v[112:115], v242 offset:36864
	s_waitcnt lgkmcnt(6)
	v_mfma_f32_16x16x32_bf16 v[16:19], v[124:127], v[140:143], v[16:19]
	ds_read_b128 v[252:255], v242 offset:38912
	v_mfma_f32_16x16x32_bf16 v[20:23], v[124:127], v[152:155], v[20:23]
	ds_read_b128 v[168:171], v240 offset:34816
	v_mfma_f32_16x16x32_bf16 v[24:27], v[124:127], v[156:159], v[24:27]
	ds_read_b128 v[244:247], v240 offset:36864
	v_mfma_f32_16x16x32_bf16 v[28:31], v[124:127], v[160:163], v[28:31]
	ds_read_b128 v[248:251], v240 offset:38912
	s_waitcnt lgkmcnt(9)
	v_mfma_f32_16x16x32_bf16 v[32:35], v[128:131], v[140:143], v[32:35]
	v_mfma_f32_16x16x32_bf16 v[36:39], v[128:131], v[152:155], v[36:39]
	v_mfma_f32_16x16x32_bf16 v[40:43], v[128:131], v[156:159], v[40:43]
	v_mfma_f32_16x16x32_bf16 v[44:47], v[128:131], v[160:163], v[44:47]
	s_waitcnt lgkmcnt(8)
	v_mfma_f32_16x16x32_bf16 v[48:51], v[132:135], v[140:143], v[48:51]
	v_mfma_f32_16x16x32_bf16 v[52:55], v[132:135], v[152:155], v[52:55]
	v_mfma_f32_16x16x32_bf16 v[56:59], v[132:135], v[156:159], v[56:59]
	v_mfma_f32_16x16x32_bf16 v[60:63], v[132:135], v[160:163], v[60:63]
	s_waitcnt lgkmcnt(6)
	v_mfma_f32_16x16x32_bf16 v[0:3], v[164:167], v[86:89], v[0:3]
	s_waitcnt lgkmcnt(5)
	v_mfma_f32_16x16x32_bf16 v[4:7], v[164:167], v[90:93], v[4:7]
	s_waitcnt lgkmcnt(4)
	v_mfma_f32_16x16x32_bf16 v[8:11], v[164:167], v[112:115], v[8:11]
	s_waitcnt lgkmcnt(3)
	v_mfma_f32_16x16x32_bf16 v[12:15], v[164:167], v[252:255], v[12:15]
	s_waitcnt lgkmcnt(2)
	v_mfma_f32_16x16x32_bf16 v[16:19], v[168:171], v[86:89], v[16:19]
	v_mfma_f32_16x16x32_bf16 v[20:23], v[168:171], v[90:93], v[20:23]
	v_mfma_f32_16x16x32_bf16 v[24:27], v[168:171], v[112:115], v[24:27]
	v_mfma_f32_16x16x32_bf16 v[28:31], v[168:171], v[252:255], v[28:31]
	s_waitcnt lgkmcnt(1)
	v_mfma_f32_16x16x32_bf16 v[32:35], v[244:247], v[86:89], v[32:35]
	v_mfma_f32_16x16x32_bf16 v[36:39], v[244:247], v[90:93], v[36:39]
	v_mfma_f32_16x16x32_bf16 v[40:43], v[244:247], v[112:115], v[40:43]
	v_mfma_f32_16x16x32_bf16 v[44:47], v[244:247], v[252:255], v[44:47]
	s_waitcnt lgkmcnt(0)
	v_mfma_f32_16x16x32_bf16 v[48:51], v[248:251], v[86:89], v[48:51]
	v_mfma_f32_16x16x32_bf16 v[52:55], v[248:251], v[90:93], v[52:55]
	v_mfma_f32_16x16x32_bf16 v[56:59], v[248:251], v[112:115], v[56:59]
	v_mfma_f32_16x16x32_bf16 v[60:63], v[248:251], v[252:255], v[60:63]
	s_waitcnt lgkmcnt(0)
	s_barrier
	s_nop 15
	ds_write_b32 v243, v0
	ds_write_b32 v243, v1 offset:528
	ds_write_b32 v243, v2 offset:1056
	ds_write_b32 v243, v3 offset:1584
	ds_write_b32 v243, v4 offset:64
	ds_write_b32 v243, v5 offset:592
	ds_write_b32 v243, v6 offset:1120
	ds_write_b32 v243, v7 offset:1648
	ds_write_b32 v243, v8 offset:128
	ds_write_b32 v243, v9 offset:656
	ds_write_b32 v243, v10 offset:1184
	ds_write_b32 v243, v11 offset:1712
	ds_write_b32 v243, v12 offset:192
	ds_write_b32 v243, v13 offset:720
	ds_write_b32 v243, v14 offset:1248
	ds_write_b32 v243, v15 offset:1776
	ds_write_b32 v243, v16 offset:8448
	ds_write_b32 v243, v17 offset:8976
	ds_write_b32 v243, v18 offset:9504
	ds_write_b32 v243, v19 offset:10032
	ds_write_b32 v243, v20 offset:8512
	ds_write_b32 v243, v21 offset:9040
	ds_write_b32 v243, v22 offset:9568
	ds_write_b32 v243, v23 offset:10096
	ds_write_b32 v243, v24 offset:8576
	ds_write_b32 v243, v25 offset:9104
	ds_write_b32 v243, v26 offset:9632
	ds_write_b32 v243, v27 offset:10160
	ds_write_b32 v243, v28 offset:8640
	ds_write_b32 v243, v29 offset:9168
	ds_write_b32 v243, v30 offset:9696
	ds_write_b32 v243, v31 offset:10224
	ds_write_b32 v243, v32 offset:16896
	ds_write_b32 v243, v33 offset:17424
	ds_write_b32 v243, v34 offset:17952
	ds_write_b32 v243, v35 offset:18480
	ds_write_b32 v243, v36 offset:16960
	ds_write_b32 v243, v37 offset:17488
	ds_write_b32 v243, v38 offset:18016
	ds_write_b32 v243, v39 offset:18544
	ds_write_b32 v243, v40 offset:17024
	ds_write_b32 v243, v41 offset:17552
	ds_write_b32 v243, v42 offset:18080
	ds_write_b32 v243, v43 offset:18608
	ds_write_b32 v243, v44 offset:17088
	ds_write_b32 v243, v45 offset:17616
	ds_write_b32 v243, v46 offset:18144
	ds_write_b32 v243, v47 offset:18672
	ds_write_b32 v243, v48 offset:25344
	ds_write_b32 v243, v49 offset:25872
	ds_write_b32 v243, v50 offset:26400
	ds_write_b32 v243, v51 offset:26928
	ds_write_b32 v243, v52 offset:25408
	ds_write_b32 v243, v53 offset:25936
	ds_write_b32 v243, v54 offset:26464
	ds_write_b32 v243, v55 offset:26992
	ds_write_b32 v243, v56 offset:25472
	ds_write_b32 v243, v57 offset:26000
	ds_write_b32 v243, v58 offset:26528
	ds_write_b32 v243, v59 offset:27056
	ds_write_b32 v243, v60 offset:25536
	ds_write_b32 v243, v61 offset:26064
	ds_write_b32 v243, v62 offset:26592
	ds_write_b32 v243, v63 offset:27120
	v_or_b32_e32 v0, s4, v78
	v_ashrrev_i32_e32 v1, 31, v0
	s_movk_i32 s4, 0x1ff
	v_cmp_lt_i32_e64 s[4:5], s4, v0
	v_lshl_add_u64 v[4:5], v[0:1], 1, s[12:13]
	v_lshl_add_u64 v[6:7], v[0:1], 2, s[38:39]
	v_or_b32_e32 v18, s6, v79
	v_or_b32_e32 v19, s6, v81
	v_or_b32_e32 v20, s6, v83
	v_or_b32_e32 v21, s6, v147
	v_mov_b32_e32 v22, v85
	v_mov_b32_e32 v23, v84
	v_mov_b32_e32 v24, v82
	v_mov_b32_e32 v25, v80
	s_waitcnt lgkmcnt(0)
	s_barrier
	s_branch .LBB0_179
